# GEMM unit head: the first K-iteration's 16 LDS fragment reads issued at the top of the head (next-unit index math runs under the LDS latency)
# baseline (speedup 1.0000x reference)
; #define PG8_STAGE(bufoff, gbase, voff) do { _Pragma("unroll") for (int _i = 0; _i < 2; ++_i) \
;         __builtin_amdgcn_global_load_lds((const unsigned*)((const char*)(gbase) + (voff)[_i]), (LAS unsigned*)(lds + (bufoff) + ldsw + _i * 8192), 16, 0, 0); } while (0)
; #define PG8_LDA(dst, b, h) do { _Pragma("unroll") for (int m = 0; m < 4; ++m) _Pragma("unroll") for (int k = 0; k < 2; ++k) dst[m][k] = *(const LAS bf16x8*)(lds + PG8_SA(b, h) + aoff + m * 2048 + k * 1024); } while (0)
; #define PG8_LDB(dst, b, h) do { _Pragma("unroll") for (int n = 0; n < 2; ++n) _Pragma("unroll") for (int k = 0; k < 2; ++k) dst[n][k] = *(const LAS bf16x8*)(lds + PG8_SB(b, h) + boff + n * 2048 + k * 1024); } while (0)
; #define PG8_SCHED __builtin_amdgcn_sched_barrier(0)
;     __device__ bool next(int i, Unit& u) const {
;         long L = (long)i * G + c;
;         if (L < nwg) {
;             int wgid = (int)L; { const int q = nwg / NXCD, r = nwg % NXCD, xcd = wgid % NXCD, off = wgid / NXCD; wgid = (xcd < r ? xcd * (q + 1) : r * (q + 1) + (xcd - r) * q) + off; }
;             const int nig = WGM * nN, gid = wgid / nig, fm = gid * WGM, gsz = (nM - fm) < WGM ? (nM - fm) : WGM;
;             u.pm = fm + ((wgid % nig) % gsz); u.pn = (wgid % nig) / gsz; u.kt0 = 0; u.nkt = nt; u.part = 0; return true;
;         }
;         L -= nwg; if (L >= (long)tail * nN * split) return false;
;         const int ks = (int)L % split, tu = (int)L / split, pairs = nt / 2, base = pairs / split, ex = pairs % split;
;         u.pm = nM + tu / nN; u.pn = tu % nN; u.kt0 = 2 * (ks * base + (ks < ex ? ks : ex)); u.nkt = 2 * (base + (ks < ex ? 1 : 0)); u.part = ks + 1; return true;
; template <class Epi>
; __device__ __forceinline__ void gemm_phase(LAS unsigned char* lds, const Gemm g, const StaticOrder& S, const Epi& E) {
;     ...
;             PG8_LDB(B0, 0, 0); PG8_SCHED; PG8_LDA(At, 0, 0); PG8_STAGE(PG8_SA(1, 1), a1 + hstepA, voffA);
.LBB0_112:
	ds_read_b128 v[146:149], v154
	ds_read_b128 v[158:161], v154 offset:1024
	ds_read_b128 v[162:165], v154 offset:2048
	ds_read_b128 v[166:169], v154 offset:3072
	ds_read_b128 v[170:173], v155
	ds_read_b128 v[174:177], v155 offset:1024
	ds_read_b128 v[178:181], v155 offset:2048
	ds_read_b128 v[182:185], v155 offset:3072
	ds_read_b128 v[186:189], v155 offset:4096
	ds_read_b128 v[190:193], v155 offset:5120
	ds_read_b128 v[194:197], v155 offset:6144
	ds_read_b128 v[198:201], v155 offset:7168
	ds_read_b128 v[202:205], v156
	ds_read_b128 v[206:209], v156 offset:1024
	ds_read_b128 v[210:213], v156 offset:2048
	ds_read_b128 v[214:217], v156 offset:3072
	s_add_i32 s72, s72, 1
	s_mul_i32 s6, s72, s75
	s_mul_hi_u32 s7, s72, s76
	s_add_i32 s7, s7, s6
	s_mul_i32 s6, s72, s76
	s_add_u32 s56, s6, s2
	s_addc_u32 s57, s7, s77
	v_cmp_gt_i64_e64 s[6:7], s[56:57], v[144:145]
	s_and_b64 vcc, exec, s[6:7]
	s_cbranch_vccnz .LBB0_118
	s_ashr_i32 s9, s56, 31
	s_lshr_b32 s9, s9, 29
	s_add_i32 s9, s56, s9
	s_and_b32 s30, s9, -8
	s_sub_i32 s33, s56, s30
	s_cmp_gt_i32 s33, 5
	s_mov_b64 s[30:31], -1
	s_cbranch_scc0 .LBB0_115
	s_mul_i32 s30, s33, 0x5a
	s_add_i32 s54, s30, 6
	s_mov_b64 s[30:31], 0

; #define PG8_STAGE(bufoff, gbase, voff) do { _Pragma("unroll") for (int _i = 0; _i < 2; ++_i) \
;         __builtin_amdgcn_global_load_lds((const unsigned*)((const char*)(gbase) + (voff)[_i]), (LAS unsigned*)(lds + (bufoff) + ldsw + _i * 8192), 16, 0, 0); } while (0)
; #define PG8_LDA(dst, b, h) do { _Pragma("unroll") for (int m = 0; m < 4; ++m) _Pragma("unroll") for (int k = 0; k < 2; ++k) dst[m][k] = *(const LAS bf16x8*)(lds + PG8_SA(b, h) + aoff + m * 2048 + k * 1024); } while (0)
; #define PG8_LDB(dst, b, h) do { _Pragma("unroll") for (int n = 0; n < 2; ++n) _Pragma("unroll") for (int k = 0; k < 2; ++k) dst[n][k] = *(const LAS bf16x8*)(lds + PG8_SB(b, h) + boff + n * 2048 + k * 1024); } while (0)
; #define PG8_WAIT_V(n) asm volatile("s_waitcnt vmcnt(" #n ")" ::: "memory")
; #define PG8_WAIT_L(n) asm volatile("s_waitcnt lgkmcnt(" #n ")" ::: "memory")
; #define PG8_BAR __builtin_amdgcn_s_barrier()
; #define PG8_SCHED __builtin_amdgcn_sched_barrier(0)
; template <class Epi>
; __device__ __forceinline__ void gemm_phase(LAS unsigned char* lds, const Gemm g, const StaticOrder& S, const Epi& E) {
;     ...
;         const char* nA = has_next ? (const char*)g.A + (size_t)nxt.pm * tstepA + (size_t)nxt.kt0 * kstep : cA; const char* nB = has_next ? (const char*)g.Bt + (size_t)nxt.pn * tstepB + (size_t)nxt.kt0 * kstep : cB;
;         const int nt = cur.nkt;
;         for (int t = 0; t < nt; t += 2) {
;             const bool last = (t == nt - 2);
;             const char* a1 = cA + (size_t)(t + 1) * kstep;
;             const char* a2 = last ? nA : cA + (size_t)(t + 2) * kstep; const char* b2 = last ? nB : cB + (size_t)(t + 2) * kstep;
;             const char* a3 = a2 + kstep; const char* b3 = b2 + kstep;
;             PG8_LDB(B0, 0, 0); PG8_SCHED; PG8_LDA(At, 0, 0); PG8_STAGE(PG8_SA(1, 1), a1 + hstepA, voffA);
;             PG8_WAIT_L(8); PG8_BAR; PG8_WAIT_L(0); PG8_MMA(0, 0, At, B0); PG8_BAR; PG8_SCHED;
;             PG8_LDB(B1, 0, 1); PG8_STAGE(PG8_SB(0, 0), b2, voffB);
;             PG8_BAR; PG8_WAIT_L(0); PG8_MMA(0, 1, At, B1); PG8_BAR;
;             PG8_LDA(At, 0, 1); PG8_STAGE(PG8_SA(0, 0), a2, voffA);
;             PG8_BAR; PG8_WAIT_L(0); PG8_MMA(1, 0, At, B0); PG8_BAR; PG8_SCHED;
;             PG8_STAGE(PG8_SB(0, 1), b2 + hstepB, voffB);
;             PG8_WAIT_V(6); PG8_BAR; PG8_MMA(1, 1, At, B1); PG8_BAR;
.LBB0_118:
	s_ashr_i32 s55, s54, 31
	v_cmp_lt_i64_e32 vcc, s[56:57], v[142:143]
	s_lshl_b64 s[56:57], s[54:55], 19
	s_add_u32 s9, s52, s56
	s_addc_u32 s31, s53, s57
	s_and_b64 s[56:57], vcc, exec
	s_cselect_b32 s57, s31, s63
	s_cselect_b32 s56, s9, s62
	s_ashr_i32 s31, s30, 31
	s_lshl_b64 s[58:59], s[30:31], 19
	s_add_u32 s9, s92, s58
	s_addc_u32 s31, s93, s59
	s_and_b64 s[58:59], vcc, exec
	s_cselect_b32 s59, s31, s65
	s_cselect_b32 s58, s9, s64
	s_add_u32 s62, s62, 0x40080
	s_addc_u32 s63, s63, 0
	s_add_u32 s9, s64, 0x100
	s_addc_u32 s31, s65, 0
	s_mov_b32 s33, -2
	s_add_u32 s55, s62, 0xfffc0080
	s_addc_u32 s61, s63, -1
	s_cmp_eq_u32 s33, 12
	s_cselect_b32 s67, s57, s61
	s_cselect_b32 s66, s56, s55
	s_cselect_b32 s65, s59, s31
	s_cselect_b32 s64, s58, s9
	s_add_i32 m0, s68, 0xc000
	v_lshl_add_u64 v[242:243], s[62:63], 0, v[138:139]
	global_load_lds_dwordx4 v[242:243], off
	s_add_i32 m0, s68, 0xe000
	v_lshl_add_u64 v[242:243], s[62:63], 0, v[140:141]
	global_load_lds_dwordx4 v[242:243], off
	s_waitcnt vmcnt(8) lgkmcnt(0)
	s_barrier
	v_mfma_f32_16x16x32_bf16 v[124:127], v[146:149], v[170:173], 0
	v_mfma_f32_16x16x32_bf16 v[120:123], v[162:165], v[170:173], 0
	v_mfma_f32_16x16x32_bf16 v[108:111], v[146:149], v[178:181], 0
	v_mfma_f32_16x16x32_bf16 v[104:107], v[162:165], v[178:181], 0
	v_mfma_f32_16x16x32_bf16 v[92:95], v[146:149], v[186:189], 0
	v_mfma_f32_16x16x32_bf16 v[88:91], v[162:165], v[186:189], 0
	v_mfma_f32_16x16x32_bf16 v[76:79], v[146:149], v[194:197], 0
	v_mfma_f32_16x16x32_bf16 v[72:75], v[162:165], v[194:197], 0
	v_mfma_f32_16x16x32_bf16 v[124:127], v[158:161], v[174:177], v[124:127]
	v_mfma_f32_16x16x32_bf16 v[120:123], v[166:169], v[174:177], v[120:123]
	v_mfma_f32_16x16x32_bf16 v[108:111], v[158:161], v[182:185], v[108:111]
	v_mfma_f32_16x16x32_bf16 v[104:107], v[166:169], v[182:185], v[104:107]
	v_mfma_f32_16x16x32_bf16 v[92:95], v[158:161], v[190:193], v[92:95]
	v_mfma_f32_16x16x32_bf16 v[88:91], v[166:169], v[190:193], v[88:91]
	v_mfma_f32_16x16x32_bf16 v[76:79], v[158:161], v[198:201], v[76:79]
	v_mfma_f32_16x16x32_bf16 v[72:75], v[166:169], v[198:201], v[72:75]
	v_mfma_f32_16x16x32_bf16 v[116:119], v[202:205], v[170:173], 0
	v_mfma_f32_16x16x32_bf16 v[112:115], v[210:213], v[170:173], 0
	v_mfma_f32_16x16x32_bf16 v[100:103], v[202:205], v[178:181], 0
	v_mfma_f32_16x16x32_bf16 v[96:99], v[210:213], v[178:181], 0
	v_mfma_f32_16x16x32_bf16 v[84:87], v[202:205], v[186:189], 0
	v_mfma_f32_16x16x32_bf16 v[80:83], v[210:213], v[186:189], 0
	v_mfma_f32_16x16x32_bf16 v[68:71], v[202:205], v[194:197], 0
	v_mfma_f32_16x16x32_bf16 v[64:67], v[210:213], v[194:197], 0
	v_mfma_f32_16x16x32_bf16 v[116:119], v[206:209], v[174:177], v[116:119]
	v_mfma_f32_16x16x32_bf16 v[112:115], v[214:217], v[174:177], v[112:115]
	v_mfma_f32_16x16x32_bf16 v[100:103], v[206:209], v[182:185], v[100:103]
	v_mfma_f32_16x16x32_bf16 v[96:99], v[214:217], v[182:185], v[96:99]
	v_mfma_f32_16x16x32_bf16 v[84:87], v[206:209], v[190:193], v[84:87]
	v_mfma_f32_16x16x32_bf16 v[80:83], v[214:217], v[190:193], v[80:83]
	v_mfma_f32_16x16x32_bf16 v[68:71], v[206:209], v[198:201], v[68:71]
	v_mfma_f32_16x16x32_bf16 v[64:67], v[214:217], v[198:201], v[64:67]
	s_barrier
	ds_read_b128 v[170:173], v155 offset:16384
	ds_read_b128 v[174:177], v155 offset:17408
	ds_read_b128 v[178:181], v155 offset:18432
	ds_read_b128 v[182:185], v155 offset:19456
	ds_read_b128 v[186:189], v155 offset:20480
	ds_read_b128 v[190:193], v155 offset:21504
	ds_read_b128 v[194:197], v155 offset:22528
	ds_read_b128 v[198:201], v155 offset:23552
	s_add_i32 s55, s78, s35
	s_mov_b32 m0, s55
	v_lshl_add_u64 v[218:219], s[64:65], 0, v[132:133]
	global_load_lds_dwordx4 v[218:219], off
	s_add_i32 m0, s55, 0x2000
	v_lshl_add_u64 v[220:221], s[64:65], 0, v[136:137]
	global_load_lds_dwordx4 v[220:221], off
	s_mov_b32 m0, s68
	v_lshl_add_u64 v[222:223], s[66:67], 0, v[130:131]
	global_load_lds_dwordx4 v[222:223], off
	s_mov_b32 m0, s69
	v_lshl_add_u64 v[224:225], s[66:67], 0, v[134:135]
	global_load_lds_dwordx4 v[224:225], off
	s_add_u32 s82, s64, 0x40000
	s_addc_u32 s83, s65, 0
	s_add_i32 s55, s79, s35
	s_mov_b32 m0, s55
	v_lshl_add_u64 v[240:241], s[82:83], 0, v[132:133]
	global_load_lds_dwordx4 v[240:241], off
	s_add_i32 m0, s55, 0x2000
	v_lshl_add_u64 v[240:241], s[82:83], 0, v[136:137]
	global_load_lds_dwordx4 v[240:241], off
	s_waitcnt vmcnt(8) lgkmcnt(0)
	s_barrier
	v_mfma_f32_16x16x32_bf16 v[60:63], v[146:149], v[170:173], 0
	v_mfma_f32_16x16x32_bf16 v[56:59], v[162:165], v[170:173], 0
	v_mfma_f32_16x16x32_bf16 v[44:47], v[146:149], v[178:181], 0
	v_mfma_f32_16x16x32_bf16 v[40:43], v[162:165], v[178:181], 0
	v_mfma_f32_16x16x32_bf16 v[28:31], v[146:149], v[186:189], 0
	v_mfma_f32_16x16x32_bf16 v[24:27], v[162:165], v[186:189], 0
	v_mfma_f32_16x16x32_bf16 v[12:15], v[146:149], v[194:197], 0
	v_mfma_f32_16x16x32_bf16 v[8:11], v[162:165], v[194:197], 0
	v_mfma_f32_16x16x32_bf16 v[60:63], v[158:161], v[174:177], v[60:63]
	v_mfma_f32_16x16x32_bf16 v[56:59], v[166:169], v[174:177], v[56:59]
	v_mfma_f32_16x16x32_bf16 v[44:47], v[158:161], v[182:185], v[44:47]
	v_mfma_f32_16x16x32_bf16 v[40:43], v[166:169], v[182:185], v[40:43]
	v_mfma_f32_16x16x32_bf16 v[28:31], v[158:161], v[190:193], v[28:31]
	v_mfma_f32_16x16x32_bf16 v[24:27], v[166:169], v[190:193], v[24:27]
	v_mfma_f32_16x16x32_bf16 v[12:15], v[158:161], v[198:201], v[12:15]
	v_mfma_f32_16x16x32_bf16 v[8:11], v[166:169], v[198:201], v[8:11]
	v_mfma_f32_16x16x32_bf16 v[52:55], v[202:205], v[170:173], 0
	v_mfma_f32_16x16x32_bf16 v[48:51], v[210:213], v[170:173], 0
	v_mfma_f32_16x16x32_bf16 v[36:39], v[202:205], v[178:181], 0
	v_mfma_f32_16x16x32_bf16 v[32:35], v[210:213], v[178:181], 0
	v_mfma_f32_16x16x32_bf16 v[20:23], v[202:205], v[186:189], 0
	v_mfma_f32_16x16x32_bf16 v[16:19], v[210:213], v[186:189], 0
	v_mfma_f32_16x16x32_bf16 v[4:7], v[202:205], v[194:197], 0
	v_mfma_f32_16x16x32_bf16 v[0:3], v[210:213], v[194:197], 0
	v_mfma_f32_16x16x32_bf16 v[52:55], v[206:209], v[174:177], v[52:55]
	v_mfma_f32_16x16x32_bf16 v[48:51], v[214:217], v[174:177], v[48:51]
	v_mfma_f32_16x16x32_bf16 v[36:39], v[206:209], v[182:185], v[36:39]
	v_mfma_f32_16x16x32_bf16 v[32:35], v[214:217], v[182:185], v[32:35]
	v_mfma_f32_16x16x32_bf16 v[20:23], v[206:209], v[190:193], v[20:23]
	v_mfma_f32_16x16x32_bf16 v[16:19], v[214:217], v[190:193], v[16:19]
	v_mfma_f32_16x16x32_bf16 v[4:7], v[206:209], v[198:201], v[4:7]
	v_mfma_f32_16x16x32_bf16 v[0:3], v[214:217], v[198:201], v[0:3]
	s_barrier
; #define PG8_STAGE(bufoff, gbase, voff) do { _Pragma("unroll") for (int _i = 0; _i < 2; ++_i) \
;         __builtin_amdgcn_global_load_lds((const unsigned*)((const char*)(gbase) + (voff)[_i]), (LAS unsigned*)(lds + (bufoff) + ldsw + _i * 8192), 16, 0, 0); } while (0)
; #define PG8_LDA(dst, b, h) do { _Pragma("unroll") for (int m = 0; m < 4; ++m) _Pragma("unroll") for (int k = 0; k < 2; ++k) dst[m][k] = *(const LAS bf16x8*)(lds + PG8_SA(b, h) + aoff + m * 2048 + k * 1024); } while (0)
; #define PG8_LDB(dst, b, h) do { _Pragma("unroll") for (int n = 0; n < 2; ++n) _Pragma("unroll") for (int k = 0; k < 2; ++k) dst[n][k] = *(const LAS bf16x8*)(lds + PG8_SB(b, h) + boff + n * 2048 + k * 1024); } while (0)
; #define PG8_MMA(ai, bj, At, Bt) do { __builtin_amdgcn_s_setprio(1); _Pragma("unroll") for (int m = 0; m < 4; ++m) _Pragma("unroll") for (int n = 0; n < 2; ++n) _Pragma("unroll") for (int k = 0; k < 2; ++k) \
;         acc[ai][bj][m][n] = __builtin_amdgcn_mfma_f32_16x16x32_bf16(Bt[n][k], At[m][k], acc[ai][bj][m][n], 0, 0, 0); __builtin_amdgcn_s_setprio(0); } while (0)
; #define PG8_WAIT_V(n) asm volatile("s_waitcnt vmcnt(" #n ")" ::: "memory")
; #define PG8_WAIT_L(n) asm volatile("s_waitcnt lgkmcnt(" #n ")" ::: "memory")
; #define PG8_BAR __builtin_amdgcn_s_barrier()
; #define PG8_SCHED __builtin_amdgcn_sched_barrier(0)
; template <class Epi>
; __device__ __forceinline__ void gemm_phase(LAS unsigned char* lds, const Gemm g, const StaticOrder& S, const Epi& E) {
;     ...
;             PG8_WAIT_V(6); PG8_BAR; PG8_MMA(1, 1, At, B1); PG8_BAR;
;             PG8_LDB(B0, 1, 0); PG8_SCHED; PG8_LDA(At, 1, 0); PG8_STAGE(PG8_SA(0, 1), a2 + hstepA, voffA);
;             PG8_WAIT_L(8); PG8_BAR; PG8_WAIT_L(0); PG8_MMA(0, 0, At, B0); PG8_BAR; PG8_SCHED;
;             PG8_LDB(B1, 1, 1); PG8_STAGE(PG8_SB(1, 0), b3, voffB);
;             PG8_BAR; PG8_WAIT_L(0); PG8_MMA(0, 1, At, B1); PG8_BAR;
;             PG8_LDA(At, 1, 1); PG8_STAGE(PG8_SA(1, 0), a3, voffA);
;             PG8_BAR; PG8_WAIT_L(0); PG8_MMA(1, 0, At, B0); PG8_BAR; PG8_SCHED;
;             PG8_STAGE(PG8_SB(1, 1), b3 + hstepB, voffB);
;             PG8_WAIT_V(6); PG8_BAR; PG8_MMA(1, 1, At, B1); PG8_BAR;
;         }
	s_add_i32 s55, 0, 0x18000
	v_add_u32_e32 v157, s55, v152
	ds_read_b128 v[146:149], v157
	ds_read_b128 v[158:161], v157 offset:1024
	ds_read_b128 v[162:165], v157 offset:2048
	ds_read_b128 v[166:169], v157 offset:3072
	ds_read_b128 v[170:173], v155 offset:32768
	ds_read_b128 v[174:177], v155 offset:33792
	ds_read_b128 v[178:181], v155 offset:34816
	ds_read_b128 v[182:185], v155 offset:35840
	ds_read_b128 v[186:189], v155 offset:36864
	ds_read_b128 v[190:193], v155 offset:37888
	ds_read_b128 v[194:197], v155 offset:38912
	ds_read_b128 v[198:201], v155 offset:39936
	s_add_i32 s98, 0, 0x1c000
	v_add_u32_e32 v246, s98, v152
	ds_read_b128 v[202:205], v246
	ds_read_b128 v[206:209], v246 offset:1024
	ds_read_b128 v[210:213], v246 offset:2048
	ds_read_b128 v[214:217], v246 offset:3072
	s_add_u32 s66, s66, 0x40000
	s_addc_u32 s67, s67, 0
	s_mov_b32 m0, s70
	v_lshl_add_u64 v[244:245], s[66:67], 0, v[130:131]
	global_load_lds_dwordx4 v[244:245], off
	s_mov_b32 m0, s71
	v_lshl_add_u64 v[244:245], s[66:67], 0, v[134:135]
	global_load_lds_dwordx4 v[244:245], off
	s_waitcnt vmcnt(8) lgkmcnt(0)
	s_barrier
	v_mfma_f32_16x16x32_bf16 v[124:127], v[146:149], v[170:173], v[124:127]
	v_mfma_f32_16x16x32_bf16 v[120:123], v[162:165], v[170:173], v[120:123]
	v_mfma_f32_16x16x32_bf16 v[108:111], v[146:149], v[178:181], v[108:111]
	v_mfma_f32_16x16x32_bf16 v[104:107], v[162:165], v[178:181], v[104:107]
	v_mfma_f32_16x16x32_bf16 v[92:95], v[146:149], v[186:189], v[92:95]
	v_mfma_f32_16x16x32_bf16 v[88:91], v[162:165], v[186:189], v[88:91]
	v_mfma_f32_16x16x32_bf16 v[76:79], v[146:149], v[194:197], v[76:79]
	v_mfma_f32_16x16x32_bf16 v[72:75], v[162:165], v[194:197], v[72:75]
	v_mfma_f32_16x16x32_bf16 v[124:127], v[158:161], v[174:177], v[124:127]
	v_mfma_f32_16x16x32_bf16 v[120:123], v[166:169], v[174:177], v[120:123]
	v_mfma_f32_16x16x32_bf16 v[108:111], v[158:161], v[182:185], v[108:111]
	v_mfma_f32_16x16x32_bf16 v[104:107], v[166:169], v[182:185], v[104:107]
	v_mfma_f32_16x16x32_bf16 v[92:95], v[158:161], v[190:193], v[92:95]
	v_mfma_f32_16x16x32_bf16 v[88:91], v[166:169], v[190:193], v[88:91]
	v_mfma_f32_16x16x32_bf16 v[76:79], v[158:161], v[198:201], v[76:79]
	v_mfma_f32_16x16x32_bf16 v[72:75], v[166:169], v[198:201], v[72:75]
	v_mfma_f32_16x16x32_bf16 v[116:119], v[202:205], v[170:173], v[116:119]
	v_mfma_f32_16x16x32_bf16 v[112:115], v[210:213], v[170:173], v[112:115]
	v_mfma_f32_16x16x32_bf16 v[100:103], v[202:205], v[178:181], v[100:103]
	v_mfma_f32_16x16x32_bf16 v[96:99], v[210:213], v[178:181], v[96:99]
	v_mfma_f32_16x16x32_bf16 v[84:87], v[202:205], v[186:189], v[84:87]
	v_mfma_f32_16x16x32_bf16 v[80:83], v[210:213], v[186:189], v[80:83]
	v_mfma_f32_16x16x32_bf16 v[68:71], v[202:205], v[194:197], v[68:71]
	v_mfma_f32_16x16x32_bf16 v[64:67], v[210:213], v[194:197], v[64:67]
	v_mfma_f32_16x16x32_bf16 v[116:119], v[206:209], v[174:177], v[116:119]
	v_mfma_f32_16x16x32_bf16 v[112:115], v[214:217], v[174:177], v[112:115]
	v_mfma_f32_16x16x32_bf16 v[100:103], v[206:209], v[182:185], v[100:103]
	v_mfma_f32_16x16x32_bf16 v[96:99], v[214:217], v[182:185], v[96:99]
	v_mfma_f32_16x16x32_bf16 v[84:87], v[206:209], v[190:193], v[84:87]
	v_mfma_f32_16x16x32_bf16 v[80:83], v[214:217], v[190:193], v[80:83]
	v_mfma_f32_16x16x32_bf16 v[68:71], v[206:209], v[198:201], v[68:71]
	v_mfma_f32_16x16x32_bf16 v[64:67], v[214:217], v[198:201], v[64:67]
	s_barrier
	ds_read_b128 v[170:173], v155 offset:49152
	ds_read_b128 v[174:177], v155 offset:50176
	ds_read_b128 v[178:181], v155 offset:51200
	ds_read_b128 v[182:185], v155 offset:52224
	ds_read_b128 v[186:189], v155 offset:53248
	ds_read_b128 v[190:193], v155 offset:54272
	ds_read_b128 v[194:197], v155 offset:55296
	ds_read_b128 v[198:201], v155 offset:56320
	s_add_i32 s55, s55, s35
	s_mov_b32 m0, s55
	v_lshl_add_u64 v[218:219], v[218:219], 0, s[28:29]
	global_load_lds_dwordx4 v[218:219], off
	s_add_i32 m0, s55, 0x2000
	v_lshl_add_u64 v[218:219], v[220:221], 0, s[28:29]
	global_load_lds_dwordx4 v[218:219], off
	s_mov_b32 m0, s73
	v_lshl_add_u64 v[218:219], v[222:223], 0, s[28:29]
	global_load_lds_dwordx4 v[218:219], off
	s_mov_b32 m0, s74
	v_lshl_add_u64 v[218:219], v[224:225], 0, s[28:29]
	global_load_lds_dwordx4 v[218:219], off
	s_add_u32 s64, s64, 0x40080
	s_addc_u32 s65, s65, 0
	s_add_i32 s55, s98, s35
	s_mov_b32 m0, s55
	v_lshl_add_u64 v[240:241], s[64:65], 0, v[132:133]
	global_load_lds_dwordx4 v[240:241], off
	s_add_i32 m0, s55, 0x2000
	v_lshl_add_u64 v[240:241], s[64:65], 0, v[136:137]
	global_load_lds_dwordx4 v[240:241], off
	s_waitcnt vmcnt(8) lgkmcnt(0)
	s_barrier
	v_mfma_f32_16x16x32_bf16 v[60:63], v[146:149], v[170:173], v[60:63]
	v_mfma_f32_16x16x32_bf16 v[56:59], v[162:165], v[170:173], v[56:59]
	v_mfma_f32_16x16x32_bf16 v[44:47], v[146:149], v[178:181], v[44:47]
	v_mfma_f32_16x16x32_bf16 v[40:43], v[162:165], v[178:181], v[40:43]
	v_mfma_f32_16x16x32_bf16 v[28:31], v[146:149], v[186:189], v[28:31]
	v_mfma_f32_16x16x32_bf16 v[24:27], v[162:165], v[186:189], v[24:27]
	v_mfma_f32_16x16x32_bf16 v[12:15], v[146:149], v[194:197], v[12:15]
	v_mfma_f32_16x16x32_bf16 v[8:11], v[162:165], v[194:197], v[8:11]
	v_mfma_f32_16x16x32_bf16 v[60:63], v[158:161], v[174:177], v[60:63]
	v_mfma_f32_16x16x32_bf16 v[56:59], v[166:169], v[174:177], v[56:59]
	v_mfma_f32_16x16x32_bf16 v[44:47], v[158:161], v[182:185], v[44:47]
	v_mfma_f32_16x16x32_bf16 v[40:43], v[166:169], v[182:185], v[40:43]
	v_mfma_f32_16x16x32_bf16 v[28:31], v[158:161], v[190:193], v[28:31]
	v_mfma_f32_16x16x32_bf16 v[24:27], v[166:169], v[190:193], v[24:27]
	v_mfma_f32_16x16x32_bf16 v[12:15], v[158:161], v[198:201], v[12:15]
	v_mfma_f32_16x16x32_bf16 v[8:11], v[166:169], v[198:201], v[8:11]
	v_mfma_f32_16x16x32_bf16 v[52:55], v[202:205], v[170:173], v[52:55]
	v_mfma_f32_16x16x32_bf16 v[48:51], v[210:213], v[170:173], v[48:51]
	v_mfma_f32_16x16x32_bf16 v[36:39], v[202:205], v[178:181], v[36:39]
	v_mfma_f32_16x16x32_bf16 v[32:35], v[210:213], v[178:181], v[32:35]
	v_mfma_f32_16x16x32_bf16 v[20:23], v[202:205], v[186:189], v[20:23]
	v_mfma_f32_16x16x32_bf16 v[16:19], v[210:213], v[186:189], v[16:19]
	v_mfma_f32_16x16x32_bf16 v[4:7], v[202:205], v[194:197], v[4:7]
	v_mfma_f32_16x16x32_bf16 v[0:3], v[210:213], v[194:197], v[0:3]
	v_mfma_f32_16x16x32_bf16 v[52:55], v[206:209], v[174:177], v[52:55]
	v_mfma_f32_16x16x32_bf16 v[48:51], v[214:217], v[174:177], v[48:51]
	v_mfma_f32_16x16x32_bf16 v[36:39], v[206:209], v[182:185], v[36:39]
	v_mfma_f32_16x16x32_bf16 v[32:35], v[214:217], v[182:185], v[32:35]
	v_mfma_f32_16x16x32_bf16 v[20:23], v[206:209], v[190:193], v[20:23]
	v_mfma_f32_16x16x32_bf16 v[16:19], v[214:217], v[190:193], v[16:19]
	v_mfma_f32_16x16x32_bf16 v[4:7], v[206:209], v[198:201], v[4:7]
	v_mfma_f32_16x16x32_bf16 v[0:3], v[214:217], v[198:201], v[0:3]
	s_add_i32 s33, s33, 2
	s_add_u32 s62, s62, 0x100
	s_addc_u32 s63, s63, 0
	s_add_u32 s9, s9, 0x100
	s_addc_u32 s31, s31, 0
	s_cmp_gt_u32 s33, 13
	s_barrier

; #define PG8_STAGE(bufoff, gbase, voff) do { _Pragma("unroll") for (int _i = 0; _i < 2; ++_i) \
;         __builtin_amdgcn_global_load_lds((const unsigned*)((const char*)(gbase) + (voff)[_i]), (LAS unsigned*)(lds + (bufoff) + ldsw + _i * 8192), 16, 0, 0); } while (0)
; #define PG8_LDA(dst, b, h) do { _Pragma("unroll") for (int m = 0; m < 4; ++m) _Pragma("unroll") for (int k = 0; k < 2; ++k) dst[m][k] = *(const LAS bf16x8*)(lds + PG8_SA(b, h) + aoff + m * 2048 + k * 1024); } while (0)
; #define PG8_LDB(dst, b, h) do { _Pragma("unroll") for (int n = 0; n < 2; ++n) _Pragma("unroll") for (int k = 0; k < 2; ++k) dst[n][k] = *(const LAS bf16x8*)(lds + PG8_SB(b, h) + boff + n * 2048 + k * 1024); } while (0)
; #define PG8_SCHED __builtin_amdgcn_sched_barrier(0)
;     __device__ bool next(int i, Unit& u) const {
;         long L = (long)i * G + c;
;         if (L < nwg) {
;             int wgid = (int)L; { const int q = nwg / NXCD, r = nwg % NXCD, xcd = wgid % NXCD, off = wgid / NXCD; wgid = (xcd < r ? xcd * (q + 1) : r * (q + 1) + (xcd - r) * q) + off; }
;             const int nig = WGM * nN, gid = wgid / nig, fm = gid * WGM, gsz = (nM - fm) < WGM ? (nM - fm) : WGM;
;             u.pm = fm + ((wgid % nig) % gsz); u.pn = (wgid % nig) / gsz; u.kt0 = 0; u.nkt = nt; u.part = 0; return true;
;         }
;         L -= nwg; if (L >= (long)tail * nN * split) return false;
;         const int ks = (int)L % split, tu = (int)L / split, pairs = nt / 2, base = pairs / split, ex = pairs % split;
;         u.pm = nM + tu / nN; u.pn = tu % nN; u.kt0 = 2 * (ks * base + (ks < ex ? ks : ex)); u.nkt = 2 * (base + (ks < ex ? 1 : 0)); u.part = ks + 1; return true;
; template <class Epi>
; __device__ __forceinline__ void gemm_phase(LAS unsigned char* lds, const Gemm g, const StaticOrder& S, const Epi& E) {
;     ...
;             PG8_LDB(B0, 0, 0); PG8_SCHED; PG8_LDA(At, 0, 0); PG8_STAGE(PG8_SA(1, 1), a1 + hstepA, voffA);
.LBB0_442:
	ds_read_b128 v[144:147], v158
	ds_read_b128 v[148:151], v158 offset:1024
	ds_read_b128 v[162:165], v158 offset:2048
	ds_read_b128 v[166:169], v158 offset:3072
	ds_read_b128 v[170:173], v159
	ds_read_b128 v[174:177], v159 offset:1024
	ds_read_b128 v[178:181], v159 offset:2048
	ds_read_b128 v[182:185], v159 offset:3072
	ds_read_b128 v[186:189], v159 offset:4096
	ds_read_b128 v[190:193], v159 offset:5120
	ds_read_b128 v[194:197], v159 offset:6144
	ds_read_b128 v[198:201], v159 offset:7168
	ds_read_b128 v[202:205], v160
	ds_read_b128 v[206:209], v160 offset:1024
	ds_read_b128 v[210:213], v160 offset:2048
	ds_read_b128 v[214:217], v160 offset:3072
	s_add_i32 s80, s80, 1
	s_mul_i32 s0, s80, s75
	s_mul_hi_u32 s1, s80, s76
	s_add_i32 s1, s1, s0
	s_mul_i32 s0, s80, s76
	s_add_u32 s0, s0, s2
	s_addc_u32 s1, s1, s77
	v_cmp_gt_i64_e32 vcc, s[0:1], v[142:143]
	s_mov_b64 s[60:61], -1
	s_cbranch_vccz .LBB0_445
	s_and_b32 s63, s1, 0x7fffffff
	s_and_b32 s62, s0, 0xffffffe0
	s_mov_b64 s[60:61], 0
	s_cmp_lg_u64 s[62:63], 0x100
	s_mov_b64 s[62:63], 0
	s_cbranch_scc1 .LBB0_445
	s_and_b32 s1, s0, 3
	s_bfe_u32 s31, s0, 0x30002
	s_cmp_gt_u32 s31, 3
	v_sub_co_u32_e64 v0, s[20:21], s31, 4
	s_cselect_b32 s56, 0x41, 64
	s_and_b64 s[20:21], s[20:21], exec
	v_readfirstlane_b32 s20, v0
	s_mov_b32 s82, 4
	s_cselect_b32 s58, s31, s20
	s_lshl_b32 s20, s1, 2
	s_add_i32 s83, s1, 1
	s_mov_b64 s[62:63], -1

; #define PG8_STAGE(bufoff, gbase, voff) do { _Pragma("unroll") for (int _i = 0; _i < 2; ++_i) \
;         __builtin_amdgcn_global_load_lds((const unsigned*)((const char*)(gbase) + (voff)[_i]), (LAS unsigned*)(lds + (bufoff) + ldsw + _i * 8192), 16, 0, 0); } while (0)
; #define PG8_LDA(dst, b, h) do { _Pragma("unroll") for (int m = 0; m < 4; ++m) _Pragma("unroll") for (int k = 0; k < 2; ++k) dst[m][k] = *(const LAS bf16x8*)(lds + PG8_SA(b, h) + aoff + m * 2048 + k * 1024); } while (0)
; #define PG8_LDB(dst, b, h) do { _Pragma("unroll") for (int n = 0; n < 2; ++n) _Pragma("unroll") for (int k = 0; k < 2; ++k) dst[n][k] = *(const LAS bf16x8*)(lds + PG8_SB(b, h) + boff + n * 2048 + k * 1024); } while (0)
; #define PG8_WAIT_V(n) asm volatile("s_waitcnt vmcnt(" #n ")" ::: "memory")
; #define PG8_WAIT_L(n) asm volatile("s_waitcnt lgkmcnt(" #n ")" ::: "memory")
; #define PG8_BAR __builtin_amdgcn_s_barrier()
; #define PG8_SCHED __builtin_amdgcn_sched_barrier(0)
; template <class Epi>
; __device__ __forceinline__ void gemm_phase(LAS unsigned char* lds, const Gemm g, const StaticOrder& S, const Epi& E) {
;     ...
;         const char* nA = has_next ? (const char*)g.A + (size_t)nxt.pm * tstepA + (size_t)nxt.kt0 * kstep : cA; const char* nB = has_next ? (const char*)g.Bt + (size_t)nxt.pn * tstepB + (size_t)nxt.kt0 * kstep : cB;
;         const int nt = cur.nkt;
;         for (int t = 0; t < nt; t += 2) {
;             const bool last = (t == nt - 2);
;             const char* a1 = cA + (size_t)(t + 1) * kstep;
;             const char* a2 = last ? nA : cA + (size_t)(t + 2) * kstep; const char* b2 = last ? nB : cB + (size_t)(t + 2) * kstep;
;             const char* a3 = a2 + kstep; const char* b3 = b2 + kstep;
;             PG8_LDB(B0, 0, 0); PG8_SCHED; PG8_LDA(At, 0, 0); PG8_STAGE(PG8_SA(1, 1), a1 + hstepA, voffA);
;             PG8_WAIT_L(8); PG8_BAR; PG8_WAIT_L(0); PG8_MMA(0, 0, At, B0); PG8_BAR; PG8_SCHED;
;             PG8_LDB(B1, 0, 1); PG8_STAGE(PG8_SB(0, 0), b2, voffB);
;             PG8_BAR; PG8_WAIT_L(0); PG8_MMA(0, 1, At, B1); PG8_BAR;
;             PG8_LDA(At, 0, 1); PG8_STAGE(PG8_SA(0, 0), a2, voffA);
;             PG8_BAR; PG8_WAIT_L(0); PG8_MMA(1, 0, At, B0); PG8_BAR; PG8_SCHED;
;             PG8_STAGE(PG8_SB(0, 1), b2 + hstepB, voffB);
;             PG8_WAIT_V(6); PG8_BAR; PG8_MMA(1, 1, At, B1); PG8_BAR;
.LBB0_455:
	s_add_i32 s21, s84, -2
	s_add_u32 s64, s64, 0x40080
	s_addc_u32 s65, s65, 0
	s_add_u32 s31, s66, 0x100
	s_addc_u32 s57, s67, 0
	s_mov_b32 s59, 0
	s_add_i32 s85, s59, 2
	s_add_u32 s66, s64, 0xfffc0080
	s_addc_u32 s67, s65, -1
	s_cmp_eq_u32 s21, s59
	s_cselect_b32 s69, s63, s67
	s_cselect_b32 s68, s62, s66
	s_cselect_b32 s67, s1, s57
	s_cselect_b32 s66, s0, s31
	s_add_i32 m0, s35, 0xc000
	v_lshl_add_u64 v[152:153], s[64:65], 0, v[138:139]
	global_load_lds_dwordx4 v[152:153], off
	s_add_i32 m0, s35, 0xe000
	v_lshl_add_u64 v[152:153], s[64:65], 0, v[140:141]
	global_load_lds_dwordx4 v[152:153], off
	s_waitcnt vmcnt(8) lgkmcnt(0)
	s_barrier
	v_mfma_f32_16x16x32_bf16 v[124:127], v[144:147], v[170:173], 0
	v_mfma_f32_16x16x32_bf16 v[120:123], v[162:165], v[170:173], 0
	v_mfma_f32_16x16x32_bf16 v[116:119], v[144:147], v[178:181], 0
	v_mfma_f32_16x16x32_bf16 v[108:111], v[162:165], v[178:181], 0
	v_mfma_f32_16x16x32_bf16 v[100:103], v[144:147], v[186:189], 0
	v_mfma_f32_16x16x32_bf16 v[92:95], v[162:165], v[186:189], 0
	v_mfma_f32_16x16x32_bf16 v[84:87], v[144:147], v[194:197], 0
	v_mfma_f32_16x16x32_bf16 v[76:79], v[162:165], v[194:197], 0
	v_mfma_f32_16x16x32_bf16 v[124:127], v[148:151], v[174:177], v[124:127]
	v_mfma_f32_16x16x32_bf16 v[120:123], v[166:169], v[174:177], v[120:123]
	v_mfma_f32_16x16x32_bf16 v[116:119], v[148:151], v[182:185], v[116:119]
	v_mfma_f32_16x16x32_bf16 v[108:111], v[166:169], v[182:185], v[108:111]
	v_mfma_f32_16x16x32_bf16 v[100:103], v[148:151], v[190:193], v[100:103]
	v_mfma_f32_16x16x32_bf16 v[92:95], v[166:169], v[190:193], v[92:95]
	v_mfma_f32_16x16x32_bf16 v[84:87], v[148:151], v[198:201], v[84:87]
	v_mfma_f32_16x16x32_bf16 v[76:79], v[166:169], v[198:201], v[76:79]
	v_mfma_f32_16x16x32_bf16 v[112:115], v[202:205], v[170:173], 0
	v_mfma_f32_16x16x32_bf16 v[104:107], v[210:213], v[170:173], 0
	v_mfma_f32_16x16x32_bf16 v[96:99], v[202:205], v[178:181], 0
	v_mfma_f32_16x16x32_bf16 v[88:91], v[210:213], v[178:181], 0
	v_mfma_f32_16x16x32_bf16 v[80:83], v[202:205], v[186:189], 0
	v_mfma_f32_16x16x32_bf16 v[72:75], v[210:213], v[186:189], 0
	v_mfma_f32_16x16x32_bf16 v[68:71], v[202:205], v[194:197], 0
	v_mfma_f32_16x16x32_bf16 v[64:67], v[210:213], v[194:197], 0
	v_mfma_f32_16x16x32_bf16 v[112:115], v[206:209], v[174:177], v[112:115]
	v_mfma_f32_16x16x32_bf16 v[104:107], v[214:217], v[174:177], v[104:107]
	v_mfma_f32_16x16x32_bf16 v[96:99], v[206:209], v[182:185], v[96:99]
	v_mfma_f32_16x16x32_bf16 v[88:91], v[214:217], v[182:185], v[88:91]
	v_mfma_f32_16x16x32_bf16 v[80:83], v[206:209], v[190:193], v[80:83]
	v_mfma_f32_16x16x32_bf16 v[72:75], v[214:217], v[190:193], v[72:75]
	v_mfma_f32_16x16x32_bf16 v[68:71], v[206:209], v[198:201], v[68:71]
	v_mfma_f32_16x16x32_bf16 v[64:67], v[214:217], v[198:201], v[64:67]
	s_barrier
	ds_read_b128 v[170:173], v159 offset:16384
	ds_read_b128 v[174:177], v159 offset:17408
	ds_read_b128 v[178:181], v159 offset:18432
	ds_read_b128 v[182:185], v159 offset:19456
	ds_read_b128 v[186:189], v159 offset:20480
	ds_read_b128 v[190:193], v159 offset:21504
	ds_read_b128 v[194:197], v159 offset:22528
	ds_read_b128 v[198:201], v159 offset:23552
	s_add_i32 s59, s78, s33
	s_mov_b32 m0, s59
	v_lshl_add_u64 v[152:153], s[66:67], 0, v[132:133]
	global_load_lds_dwordx4 v[152:153], off
	s_add_i32 m0, s59, 0x2000
	v_lshl_add_u64 v[218:219], s[66:67], 0, v[136:137]
	global_load_lds_dwordx4 v[218:219], off
	s_mov_b32 m0, s35
	v_lshl_add_u64 v[220:221], s[68:69], 0, v[130:131]
	global_load_lds_dwordx4 v[220:221], off
	s_mov_b32 m0, s70
	v_lshl_add_u64 v[222:223], s[68:69], 0, v[134:135]
	global_load_lds_dwordx4 v[222:223], off
	s_add_u32 s86, s66, 0x40000
	s_addc_u32 s87, s67, 0
	s_add_i32 s59, s79, s33
	s_mov_b32 m0, s59
	v_lshl_add_u64 v[240:241], s[86:87], 0, v[132:133]
	global_load_lds_dwordx4 v[240:241], off
	s_add_i32 m0, s59, 0x2000
	v_lshl_add_u64 v[240:241], s[86:87], 0, v[136:137]
	global_load_lds_dwordx4 v[240:241], off
	s_waitcnt vmcnt(8) lgkmcnt(0)
	s_barrier
	v_mfma_f32_16x16x32_bf16 v[60:63], v[144:147], v[170:173], 0
	v_mfma_f32_16x16x32_bf16 v[56:59], v[162:165], v[170:173], 0
	v_mfma_f32_16x16x32_bf16 v[52:55], v[144:147], v[178:181], 0
	v_mfma_f32_16x16x32_bf16 v[44:47], v[162:165], v[178:181], 0
	v_mfma_f32_16x16x32_bf16 v[36:39], v[144:147], v[186:189], 0
	v_mfma_f32_16x16x32_bf16 v[28:31], v[162:165], v[186:189], 0
	v_mfma_f32_16x16x32_bf16 v[20:23], v[144:147], v[194:197], 0
	v_mfma_f32_16x16x32_bf16 v[12:15], v[162:165], v[194:197], 0
	v_mfma_f32_16x16x32_bf16 v[60:63], v[148:151], v[174:177], v[60:63]
	v_mfma_f32_16x16x32_bf16 v[56:59], v[166:169], v[174:177], v[56:59]
	v_mfma_f32_16x16x32_bf16 v[52:55], v[148:151], v[182:185], v[52:55]
	v_mfma_f32_16x16x32_bf16 v[44:47], v[166:169], v[182:185], v[44:47]
	v_mfma_f32_16x16x32_bf16 v[36:39], v[148:151], v[190:193], v[36:39]
	v_mfma_f32_16x16x32_bf16 v[28:31], v[166:169], v[190:193], v[28:31]
	v_mfma_f32_16x16x32_bf16 v[20:23], v[148:151], v[198:201], v[20:23]
	v_mfma_f32_16x16x32_bf16 v[12:15], v[166:169], v[198:201], v[12:15]
	v_mfma_f32_16x16x32_bf16 v[48:51], v[202:205], v[170:173], 0
	v_mfma_f32_16x16x32_bf16 v[40:43], v[210:213], v[170:173], 0
	v_mfma_f32_16x16x32_bf16 v[32:35], v[202:205], v[178:181], 0
	v_mfma_f32_16x16x32_bf16 v[24:27], v[210:213], v[178:181], 0
	v_mfma_f32_16x16x32_bf16 v[16:19], v[202:205], v[186:189], 0
	v_mfma_f32_16x16x32_bf16 v[8:11], v[210:213], v[186:189], 0
	v_mfma_f32_16x16x32_bf16 v[4:7], v[202:205], v[194:197], 0
	v_mfma_f32_16x16x32_bf16 v[0:3], v[210:213], v[194:197], 0
	v_mfma_f32_16x16x32_bf16 v[48:51], v[206:209], v[174:177], v[48:51]
	v_mfma_f32_16x16x32_bf16 v[40:43], v[214:217], v[174:177], v[40:43]
	v_mfma_f32_16x16x32_bf16 v[32:35], v[206:209], v[182:185], v[32:35]
	v_mfma_f32_16x16x32_bf16 v[24:27], v[214:217], v[182:185], v[24:27]
	v_mfma_f32_16x16x32_bf16 v[16:19], v[206:209], v[190:193], v[16:19]
	v_mfma_f32_16x16x32_bf16 v[8:11], v[214:217], v[190:193], v[8:11]
	v_mfma_f32_16x16x32_bf16 v[4:7], v[206:209], v[198:201], v[4:7]
	v_mfma_f32_16x16x32_bf16 v[0:3], v[214:217], v[198:201], v[0:3]
	s_barrier
; #define PG8_STAGE(bufoff, gbase, voff) do { _Pragma("unroll") for (int _i = 0; _i < 2; ++_i) \
;         __builtin_amdgcn_global_load_lds((const unsigned*)((const char*)(gbase) + (voff)[_i]), (LAS unsigned*)(lds + (bufoff) + ldsw + _i * 8192), 16, 0, 0); } while (0)
; #define PG8_LDA(dst, b, h) do { _Pragma("unroll") for (int m = 0; m < 4; ++m) _Pragma("unroll") for (int k = 0; k < 2; ++k) dst[m][k] = *(const LAS bf16x8*)(lds + PG8_SA(b, h) + aoff + m * 2048 + k * 1024); } while (0)
; #define PG8_LDB(dst, b, h) do { _Pragma("unroll") for (int n = 0; n < 2; ++n) _Pragma("unroll") for (int k = 0; k < 2; ++k) dst[n][k] = *(const LAS bf16x8*)(lds + PG8_SB(b, h) + boff + n * 2048 + k * 1024); } while (0)
; #define PG8_MMA(ai, bj, At, Bt) do { __builtin_amdgcn_s_setprio(1); _Pragma("unroll") for (int m = 0; m < 4; ++m) _Pragma("unroll") for (int n = 0; n < 2; ++n) _Pragma("unroll") for (int k = 0; k < 2; ++k) \
;         acc[ai][bj][m][n] = __builtin_amdgcn_mfma_f32_16x16x32_bf16(Bt[n][k], At[m][k], acc[ai][bj][m][n], 0, 0, 0); __builtin_amdgcn_s_setprio(0); } while (0)
; #define PG8_WAIT_V(n) asm volatile("s_waitcnt vmcnt(" #n ")" ::: "memory")
; #define PG8_WAIT_L(n) asm volatile("s_waitcnt lgkmcnt(" #n ")" ::: "memory")
; #define PG8_BAR __builtin_amdgcn_s_barrier()
; #define PG8_SCHED __builtin_amdgcn_sched_barrier(0)
; template <class Epi>
; __device__ __forceinline__ void gemm_phase(LAS unsigned char* lds, const Gemm g, const StaticOrder& S, const Epi& E) {
;     ...
;             PG8_LDB(B0, 1, 0); PG8_SCHED; PG8_LDA(At, 1, 0); PG8_STAGE(PG8_SA(0, 1), a2 + hstepA, voffA);
;             PG8_WAIT_L(8); PG8_BAR; PG8_WAIT_L(0); PG8_MMA(0, 0, At, B0); PG8_BAR; PG8_SCHED;
;             PG8_LDB(B1, 1, 1); PG8_STAGE(PG8_SB(1, 0), b3, voffB);
;             PG8_BAR; PG8_WAIT_L(0); PG8_MMA(0, 1, At, B1); PG8_BAR;
;             PG8_LDA(At, 1, 1); PG8_STAGE(PG8_SA(1, 0), a3, voffA);
;             PG8_BAR; PG8_WAIT_L(0); PG8_MMA(1, 0, At, B0); PG8_BAR; PG8_SCHED;
;             PG8_STAGE(PG8_SB(1, 1), b3 + hstepB, voffB);
;             PG8_WAIT_V(6); PG8_BAR; PG8_MMA(1, 1, At, B1); PG8_BAR;
	s_add_i32 s59, 0, 0x18000
	v_add_u32_e32 v161, s59, v156
	ds_read_b128 v[144:147], v161
	ds_read_b128 v[148:151], v161 offset:1024
	ds_read_b128 v[162:165], v161 offset:2048
	ds_read_b128 v[166:169], v161 offset:3072
	ds_read_b128 v[170:173], v159 offset:32768
	ds_read_b128 v[174:177], v159 offset:33792
	ds_read_b128 v[178:181], v159 offset:34816
	ds_read_b128 v[182:185], v159 offset:35840
	ds_read_b128 v[186:189], v159 offset:36864
	ds_read_b128 v[190:193], v159 offset:37888
	ds_read_b128 v[194:197], v159 offset:38912
	ds_read_b128 v[198:201], v159 offset:39936
	s_add_i32 s98, 0, 0x1c000
	v_add_u32_e32 v246, s98, v156
	ds_read_b128 v[202:205], v246
	ds_read_b128 v[206:209], v246 offset:1024
	ds_read_b128 v[210:213], v246 offset:2048
	ds_read_b128 v[214:217], v246 offset:3072
	s_add_u32 s68, s68, 0x40000
	s_addc_u32 s69, s69, 0
	s_mov_b32 m0, s71
	v_lshl_add_u64 v[244:245], s[68:69], 0, v[130:131]
	global_load_lds_dwordx4 v[244:245], off
	s_mov_b32 m0, s72
	v_lshl_add_u64 v[244:245], s[68:69], 0, v[134:135]
	global_load_lds_dwordx4 v[244:245], off
	s_waitcnt vmcnt(8) lgkmcnt(0)
	s_barrier
	v_mfma_f32_16x16x32_bf16 v[124:127], v[144:147], v[170:173], v[124:127]
	v_mfma_f32_16x16x32_bf16 v[120:123], v[162:165], v[170:173], v[120:123]
	v_mfma_f32_16x16x32_bf16 v[116:119], v[144:147], v[178:181], v[116:119]
	v_mfma_f32_16x16x32_bf16 v[108:111], v[162:165], v[178:181], v[108:111]
	v_mfma_f32_16x16x32_bf16 v[100:103], v[144:147], v[186:189], v[100:103]
	v_mfma_f32_16x16x32_bf16 v[92:95], v[162:165], v[186:189], v[92:95]
	v_mfma_f32_16x16x32_bf16 v[84:87], v[144:147], v[194:197], v[84:87]
	v_mfma_f32_16x16x32_bf16 v[76:79], v[162:165], v[194:197], v[76:79]
	v_mfma_f32_16x16x32_bf16 v[124:127], v[148:151], v[174:177], v[124:127]
	v_mfma_f32_16x16x32_bf16 v[120:123], v[166:169], v[174:177], v[120:123]
	v_mfma_f32_16x16x32_bf16 v[116:119], v[148:151], v[182:185], v[116:119]
	v_mfma_f32_16x16x32_bf16 v[108:111], v[166:169], v[182:185], v[108:111]
	v_mfma_f32_16x16x32_bf16 v[100:103], v[148:151], v[190:193], v[100:103]
	v_mfma_f32_16x16x32_bf16 v[92:95], v[166:169], v[190:193], v[92:95]
	v_mfma_f32_16x16x32_bf16 v[84:87], v[148:151], v[198:201], v[84:87]
	v_mfma_f32_16x16x32_bf16 v[76:79], v[166:169], v[198:201], v[76:79]
	v_mfma_f32_16x16x32_bf16 v[112:115], v[202:205], v[170:173], v[112:115]
	v_mfma_f32_16x16x32_bf16 v[104:107], v[210:213], v[170:173], v[104:107]
	v_mfma_f32_16x16x32_bf16 v[96:99], v[202:205], v[178:181], v[96:99]
	v_mfma_f32_16x16x32_bf16 v[88:91], v[210:213], v[178:181], v[88:91]
	v_mfma_f32_16x16x32_bf16 v[80:83], v[202:205], v[186:189], v[80:83]
	v_mfma_f32_16x16x32_bf16 v[72:75], v[210:213], v[186:189], v[72:75]
	v_mfma_f32_16x16x32_bf16 v[68:71], v[202:205], v[194:197], v[68:71]
	v_mfma_f32_16x16x32_bf16 v[64:67], v[210:213], v[194:197], v[64:67]
	v_mfma_f32_16x16x32_bf16 v[112:115], v[206:209], v[174:177], v[112:115]
	v_mfma_f32_16x16x32_bf16 v[104:107], v[214:217], v[174:177], v[104:107]
	v_mfma_f32_16x16x32_bf16 v[96:99], v[206:209], v[182:185], v[96:99]
	v_mfma_f32_16x16x32_bf16 v[88:91], v[214:217], v[182:185], v[88:91]
	v_mfma_f32_16x16x32_bf16 v[80:83], v[206:209], v[190:193], v[80:83]
	v_mfma_f32_16x16x32_bf16 v[72:75], v[214:217], v[190:193], v[72:75]
	v_mfma_f32_16x16x32_bf16 v[68:71], v[206:209], v[198:201], v[68:71]
	v_mfma_f32_16x16x32_bf16 v[64:67], v[214:217], v[198:201], v[64:67]
	s_barrier
	ds_read_b128 v[170:173], v159 offset:49152
	ds_read_b128 v[174:177], v159 offset:50176
	ds_read_b128 v[178:181], v159 offset:51200
	ds_read_b128 v[182:185], v159 offset:52224
	ds_read_b128 v[186:189], v159 offset:53248
	ds_read_b128 v[190:193], v159 offset:54272
	ds_read_b128 v[194:197], v159 offset:55296
	ds_read_b128 v[198:201], v159 offset:56320
	s_add_i32 s59, s59, s33
	s_mov_b32 m0, s59
	v_lshl_add_u64 v[152:153], v[152:153], 0, s[12:13]
	global_load_lds_dwordx4 v[152:153], off
	s_add_i32 m0, s59, 0x2000
	v_lshl_add_u64 v[152:153], v[218:219], 0, s[12:13]
	global_load_lds_dwordx4 v[152:153], off
	s_mov_b32 m0, s73
	v_lshl_add_u64 v[152:153], v[220:221], 0, s[12:13]
	global_load_lds_dwordx4 v[152:153], off
	s_mov_b32 m0, s74
	v_lshl_add_u64 v[152:153], v[222:223], 0, s[12:13]
	global_load_lds_dwordx4 v[152:153], off
	s_add_u32 s66, s66, 0x40080
	s_addc_u32 s67, s67, 0
	s_add_i32 s59, s98, s33
	s_mov_b32 m0, s59
	v_lshl_add_u64 v[240:241], s[66:67], 0, v[132:133]
	global_load_lds_dwordx4 v[240:241], off
	s_add_i32 m0, s59, 0x2000
	v_lshl_add_u64 v[240:241], s[66:67], 0, v[136:137]
	global_load_lds_dwordx4 v[240:241], off
	s_waitcnt vmcnt(8) lgkmcnt(0)
	s_barrier
	v_mfma_f32_16x16x32_bf16 v[60:63], v[144:147], v[170:173], v[60:63]
	v_mfma_f32_16x16x32_bf16 v[56:59], v[162:165], v[170:173], v[56:59]
	v_mfma_f32_16x16x32_bf16 v[52:55], v[144:147], v[178:181], v[52:55]
	v_mfma_f32_16x16x32_bf16 v[44:47], v[162:165], v[178:181], v[44:47]
	v_mfma_f32_16x16x32_bf16 v[36:39], v[144:147], v[186:189], v[36:39]
	v_mfma_f32_16x16x32_bf16 v[28:31], v[162:165], v[186:189], v[28:31]
	v_mfma_f32_16x16x32_bf16 v[20:23], v[144:147], v[194:197], v[20:23]
	v_mfma_f32_16x16x32_bf16 v[12:15], v[162:165], v[194:197], v[12:15]
	v_mfma_f32_16x16x32_bf16 v[60:63], v[148:151], v[174:177], v[60:63]
	v_mfma_f32_16x16x32_bf16 v[56:59], v[166:169], v[174:177], v[56:59]
	v_mfma_f32_16x16x32_bf16 v[52:55], v[148:151], v[182:185], v[52:55]
	v_mfma_f32_16x16x32_bf16 v[44:47], v[166:169], v[182:185], v[44:47]
	v_mfma_f32_16x16x32_bf16 v[36:39], v[148:151], v[190:193], v[36:39]
	v_mfma_f32_16x16x32_bf16 v[28:31], v[166:169], v[190:193], v[28:31]
	v_mfma_f32_16x16x32_bf16 v[20:23], v[148:151], v[198:201], v[20:23]
	v_mfma_f32_16x16x32_bf16 v[12:15], v[166:169], v[198:201], v[12:15]
	v_mfma_f32_16x16x32_bf16 v[48:51], v[202:205], v[170:173], v[48:51]
	v_mfma_f32_16x16x32_bf16 v[40:43], v[210:213], v[170:173], v[40:43]
	v_mfma_f32_16x16x32_bf16 v[32:35], v[202:205], v[178:181], v[32:35]
	v_mfma_f32_16x16x32_bf16 v[24:27], v[210:213], v[178:181], v[24:27]
	v_mfma_f32_16x16x32_bf16 v[16:19], v[202:205], v[186:189], v[16:19]
	v_mfma_f32_16x16x32_bf16 v[8:11], v[210:213], v[186:189], v[8:11]
	v_mfma_f32_16x16x32_bf16 v[4:7], v[202:205], v[194:197], v[4:7]
	v_mfma_f32_16x16x32_bf16 v[0:3], v[210:213], v[194:197], v[0:3]
	v_mfma_f32_16x16x32_bf16 v[48:51], v[206:209], v[174:177], v[48:51]
	v_mfma_f32_16x16x32_bf16 v[40:43], v[214:217], v[174:177], v[40:43]
	v_mfma_f32_16x16x32_bf16 v[32:35], v[206:209], v[182:185], v[32:35]
	v_mfma_f32_16x16x32_bf16 v[24:27], v[214:217], v[182:185], v[24:27]
	v_mfma_f32_16x16x32_bf16 v[16:19], v[206:209], v[190:193], v[16:19]
	v_mfma_f32_16x16x32_bf16 v[8:11], v[214:217], v[190:193], v[8:11]
	v_mfma_f32_16x16x32_bf16 v[4:7], v[206:209], v[198:201], v[4:7]
	v_mfma_f32_16x16x32_bf16 v[0:3], v[214:217], v[198:201], v[0:3]
	s_add_u32 s64, s64, 0x100
	s_addc_u32 s65, s65, 0
	s_add_u32 s31, s31, 0x100
	s_addc_u32 s57, s57, 0
	s_cmp_ge_i32 s85, s84
	s_mov_b32 s59, s85
	s_barrier

; #define PG8_STAGE(bufoff, gbase, voff) do { _Pragma("unroll") for (int _i = 0; _i < 2; ++_i) \
;         __builtin_amdgcn_global_load_lds((const unsigned*)((const char*)(gbase) + (voff)[_i]), (LAS unsigned*)(lds + (bufoff) + ldsw + _i * 8192), 16, 0, 0); } while (0)
; #define PG8_LDA(dst, b, h) do { _Pragma("unroll") for (int m = 0; m < 4; ++m) _Pragma("unroll") for (int k = 0; k < 2; ++k) dst[m][k] = *(const LAS bf16x8*)(lds + PG8_SA(b, h) + aoff + m * 2048 + k * 1024); } while (0)
; #define PG8_LDB(dst, b, h) do { _Pragma("unroll") for (int n = 0; n < 2; ++n) _Pragma("unroll") for (int k = 0; k < 2; ++k) dst[n][k] = *(const LAS bf16x8*)(lds + PG8_SB(b, h) + boff + n * 2048 + k * 1024); } while (0)
; #define PG8_MMA(ai, bj, At, Bt) do { __builtin_amdgcn_s_setprio(1); _Pragma("unroll") for (int m = 0; m < 4; ++m) _Pragma("unroll") for (int n = 0; n < 2; ++n) _Pragma("unroll") for (int k = 0; k < 2; ++k) \
;         acc[ai][bj][m][n] = __builtin_amdgcn_mfma_f32_16x16x32_bf16(Bt[n][k], At[m][k], acc[ai][bj][m][n], 0, 0, 0); __builtin_amdgcn_s_setprio(0); } while (0)
; #define PG8_WAIT_L(n) asm volatile("s_waitcnt lgkmcnt(" #n ")" ::: "memory")
; #define PG8_BAR __builtin_amdgcn_s_barrier()
; #define PG8_SCHED __builtin_amdgcn_sched_barrier(0)
;     __device__ bool next(int i, Unit& u) const {
;         long L = (long)i * G + c;
;         if (L < nwg) {
;             int wgid = (int)L; { const int q = nwg / NXCD, r = nwg % NXCD, xcd = wgid % NXCD, off = wgid / NXCD; wgid = (xcd < r ? xcd * (q + 1) : r * (q + 1) + (xcd - r) * q) + off; }
;             const int nig = WGM * nN, gid = wgid / nig, fm = gid * WGM, gsz = (nM - fm) < WGM ? (nM - fm) : WGM;
;             u.pm = fm + ((wgid % nig) % gsz); u.pn = (wgid % nig) / gsz; u.kt0 = 0; u.nkt = nt; u.part = 0; return true;
; template <class Epi>
; __device__ __forceinline__ void gemm_phase(LAS unsigned char* lds, const Gemm g, const StaticOrder& S, const Epi& E) {
;     ...
;             PG8_LDB(B0, 0, 0); PG8_SCHED; PG8_LDA(At, 0, 0); PG8_STAGE(PG8_SA(1, 1), a1 + hstepA, voffA);
;             PG8_WAIT_L(8); PG8_BAR; PG8_WAIT_L(0); PG8_MMA(0, 0, At, B0); PG8_BAR; PG8_SCHED;
;             PG8_LDB(B1, 0, 1); PG8_STAGE(PG8_SB(0, 0), b2, voffB);
.LBB0_675:
	ds_read_b128 v[152:155], v159
	ds_read_b128 v[162:165], v159 offset:1024
	ds_read_b128 v[166:169], v159 offset:2048
	ds_read_b128 v[170:173], v159 offset:3072
	ds_read_b128 v[174:177], v160
	ds_read_b128 v[178:181], v160 offset:1024
	ds_read_b128 v[182:185], v160 offset:2048
	ds_read_b128 v[186:189], v160 offset:3072
	ds_read_b128 v[190:193], v160 offset:4096
	ds_read_b128 v[194:197], v160 offset:5120
	ds_read_b128 v[198:201], v160 offset:6144
	ds_read_b128 v[202:205], v160 offset:7168
	ds_read_b128 v[206:209], v161
	ds_read_b128 v[210:213], v161 offset:1024
	ds_read_b128 v[214:217], v161 offset:2048
	ds_read_b128 v[218:221], v161 offset:3072
	s_add_i32 s69, s69, 1
	s_mul_i32 s6, s69, s73
	s_mul_hi_u32 s7, s69, s74
	s_add_i32 s7, s7, s6
	s_mul_i32 s6, s69, s74
	s_add_u32 s40, s6, s2
	s_addc_u32 s41, s7, s21
	v_cmp_gt_i64_e64 s[6:7], s[40:41], v[150:151]
	s_and_b64 vcc, exec, s[6:7]
	s_cbranch_vccnz .LBB0_681
	s_ashr_i32 s36, s40, 31
	s_lshr_b32 s36, s36, 29
	s_add_i32 s38, s40, s36
	s_and_b32 s36, s38, -8
	s_sub_i32 s39, s40, s36
	s_cmp_gt_i32 s39, 3
	s_mov_b64 s[36:37], -1
	s_cbranch_scc0 .LBB0_678
	s_mul_i32 s36, s39, 0xb5
	s_add_i32 s56, s36, 4
	s_mov_b64 s[36:37], 0

; #define PG8_STAGE(bufoff, gbase, voff) do { _Pragma("unroll") for (int _i = 0; _i < 2; ++_i) \
;         __builtin_amdgcn_global_load_lds((const unsigned*)((const char*)(gbase) + (voff)[_i]), (LAS unsigned*)(lds + (bufoff) + ldsw + _i * 8192), 16, 0, 0); } while (0)
; #define PG8_LDA(dst, b, h) do { _Pragma("unroll") for (int m = 0; m < 4; ++m) _Pragma("unroll") for (int k = 0; k < 2; ++k) dst[m][k] = *(const LAS bf16x8*)(lds + PG8_SA(b, h) + aoff + m * 2048 + k * 1024); } while (0)
; #define PG8_LDB(dst, b, h) do { _Pragma("unroll") for (int n = 0; n < 2; ++n) _Pragma("unroll") for (int k = 0; k < 2; ++k) dst[n][k] = *(const LAS bf16x8*)(lds + PG8_SB(b, h) + boff + n * 2048 + k * 1024); } while (0)
; #define PG8_WAIT_V(n) asm volatile("s_waitcnt vmcnt(" #n ")" ::: "memory")
; #define PG8_WAIT_L(n) asm volatile("s_waitcnt lgkmcnt(" #n ")" ::: "memory")
; #define PG8_BAR __builtin_amdgcn_s_barrier()
; #define PG8_SCHED __builtin_amdgcn_sched_barrier(0)
; template <class Epi>
; __device__ __forceinline__ void gemm_phase(LAS unsigned char* lds, const Gemm g, const StaticOrder& S, const Epi& E) {
;     ...
;         const char* nA = has_next ? (const char*)g.A + (size_t)nxt.pm * tstepA + (size_t)nxt.kt0 * kstep : cA; const char* nB = has_next ? (const char*)g.Bt + (size_t)nxt.pn * tstepB + (size_t)nxt.kt0 * kstep : cB;
;         const int nt = cur.nkt;
;         for (int t = 0; t < nt; t += 2) {
;             const bool last = (t == nt - 2);
;             const char* a1 = cA + (size_t)(t + 1) * kstep;
;             const char* a2 = last ? nA : cA + (size_t)(t + 2) * kstep; const char* b2 = last ? nB : cB + (size_t)(t + 2) * kstep;
;             const char* a3 = a2 + kstep; const char* b3 = b2 + kstep;
;             PG8_LDB(B0, 0, 0); PG8_SCHED; PG8_LDA(At, 0, 0); PG8_STAGE(PG8_SA(1, 1), a1 + hstepA, voffA);
;             PG8_WAIT_L(8); PG8_BAR; PG8_WAIT_L(0); PG8_MMA(0, 0, At, B0); PG8_BAR; PG8_SCHED;
;             PG8_LDB(B1, 0, 1); PG8_STAGE(PG8_SB(0, 0), b2, voffB);
;             PG8_BAR; PG8_WAIT_L(0); PG8_MMA(0, 1, At, B1); PG8_BAR;
;             PG8_LDA(At, 0, 1); PG8_STAGE(PG8_SA(0, 0), a2, voffA);
;             PG8_BAR; PG8_WAIT_L(0); PG8_MMA(1, 0, At, B0); PG8_BAR; PG8_SCHED;
;             PG8_STAGE(PG8_SB(0, 1), b2 + hstepB, voffB);
;             PG8_WAIT_V(6); PG8_BAR; PG8_MMA(1, 1, At, B1); PG8_BAR;
.LBB0_681:
	s_ashr_i32 s39, s38, 31
	v_cmp_lt_i64_e32 vcc, s[40:41], v[148:149]
	s_lshl_b64 s[40:41], s[38:39], 19
	s_add_u32 s37, s52, s40
	s_addc_u32 s39, s53, s41
	s_and_b64 s[40:41], vcc, exec
	s_cselect_b32 s41, s39, s61
	s_cselect_b32 s40, s37, s60
	s_ashr_i32 s37, s36, 31
	s_lshl_b64 s[56:57], s[36:37], 19
	s_add_u32 s37, s54, s56
	s_addc_u32 s39, s55, s57
	s_and_b64 s[56:57], vcc, exec
	s_cselect_b32 s57, s39, s63
	s_cselect_b32 s56, s37, s62
	s_add_u32 s60, s60, 0x40080
	s_addc_u32 s61, s61, 0
	s_add_u32 s37, s62, 0x100
	s_addc_u32 s39, s63, 0
	s_mov_b32 s78, -2
	s_add_u32 s62, s60, 0xfffc0080
	s_addc_u32 s63, s61, -1
	s_cmp_eq_u32 s78, 12
	s_cselect_b32 s65, s41, s63
	s_cselect_b32 s64, s40, s62
	s_cselect_b32 s63, s57, s39
	s_cselect_b32 s62, s56, s37
	s_add_i32 m0, s35, 0xc000
	v_lshl_add_u64 v[242:243], s[60:61], 0, v[144:145]
	global_load_lds_dwordx4 v[242:243], off
	s_add_i32 m0, s35, 0xe000
	v_lshl_add_u64 v[242:243], s[60:61], 0, v[146:147]
	global_load_lds_dwordx4 v[242:243], off
	s_waitcnt vmcnt(8) lgkmcnt(0)
	s_barrier
	v_mfma_f32_16x16x32_bf16 v[124:127], v[152:155], v[174:177], 0
	v_mfma_f32_16x16x32_bf16 v[120:123], v[166:169], v[174:177], 0
	v_mfma_f32_16x16x32_bf16 v[116:119], v[152:155], v[182:185], 0
	v_mfma_f32_16x16x32_bf16 v[108:111], v[166:169], v[182:185], 0
	v_mfma_f32_16x16x32_bf16 v[100:103], v[152:155], v[190:193], 0
	v_mfma_f32_16x16x32_bf16 v[92:95], v[166:169], v[190:193], 0
	v_mfma_f32_16x16x32_bf16 v[84:87], v[152:155], v[198:201], 0
	v_mfma_f32_16x16x32_bf16 v[76:79], v[166:169], v[198:201], 0
	v_mfma_f32_16x16x32_bf16 v[124:127], v[162:165], v[178:181], v[124:127]
	v_mfma_f32_16x16x32_bf16 v[120:123], v[170:173], v[178:181], v[120:123]
	v_mfma_f32_16x16x32_bf16 v[116:119], v[162:165], v[186:189], v[116:119]
	v_mfma_f32_16x16x32_bf16 v[108:111], v[170:173], v[186:189], v[108:111]
	v_mfma_f32_16x16x32_bf16 v[100:103], v[162:165], v[194:197], v[100:103]
	v_mfma_f32_16x16x32_bf16 v[92:95], v[170:173], v[194:197], v[92:95]
	v_mfma_f32_16x16x32_bf16 v[84:87], v[162:165], v[202:205], v[84:87]
	v_mfma_f32_16x16x32_bf16 v[76:79], v[170:173], v[202:205], v[76:79]
	v_mfma_f32_16x16x32_bf16 v[112:115], v[206:209], v[174:177], 0
	v_mfma_f32_16x16x32_bf16 v[104:107], v[214:217], v[174:177], 0
	v_mfma_f32_16x16x32_bf16 v[96:99], v[206:209], v[182:185], 0
	v_mfma_f32_16x16x32_bf16 v[88:91], v[214:217], v[182:185], 0
	v_mfma_f32_16x16x32_bf16 v[80:83], v[206:209], v[190:193], 0
	v_mfma_f32_16x16x32_bf16 v[72:75], v[214:217], v[190:193], 0
	v_mfma_f32_16x16x32_bf16 v[68:71], v[206:209], v[198:201], 0
	v_mfma_f32_16x16x32_bf16 v[64:67], v[214:217], v[198:201], 0
	v_mfma_f32_16x16x32_bf16 v[112:115], v[210:213], v[178:181], v[112:115]
	v_mfma_f32_16x16x32_bf16 v[104:107], v[218:221], v[178:181], v[104:107]
	v_mfma_f32_16x16x32_bf16 v[96:99], v[210:213], v[186:189], v[96:99]
	v_mfma_f32_16x16x32_bf16 v[88:91], v[218:221], v[186:189], v[88:91]
	v_mfma_f32_16x16x32_bf16 v[80:83], v[210:213], v[194:197], v[80:83]
	v_mfma_f32_16x16x32_bf16 v[72:75], v[218:221], v[194:197], v[72:75]
	v_mfma_f32_16x16x32_bf16 v[68:71], v[210:213], v[202:205], v[68:71]
	v_mfma_f32_16x16x32_bf16 v[64:67], v[218:221], v[202:205], v[64:67]
	s_barrier
	ds_read_b128 v[174:177], v160 offset:16384
	ds_read_b128 v[178:181], v160 offset:17408
	ds_read_b128 v[182:185], v160 offset:18432
	ds_read_b128 v[186:189], v160 offset:19456
	ds_read_b128 v[190:193], v160 offset:20480
	ds_read_b128 v[194:197], v160 offset:21504
	ds_read_b128 v[198:201], v160 offset:22528
	ds_read_b128 v[202:205], v160 offset:23552
	s_add_i32 s79, s75, s33
	s_mov_b32 m0, s79
	v_lshl_add_u64 v[222:223], s[62:63], 0, v[138:139]
	global_load_lds_dwordx4 v[222:223], off
	s_add_i32 m0, s79, 0x2000
	v_lshl_add_u64 v[224:225], s[62:63], 0, v[142:143]
	global_load_lds_dwordx4 v[224:225], off
	s_mov_b32 m0, s35
	v_lshl_add_u64 v[226:227], s[64:65], 0, v[136:137]
	global_load_lds_dwordx4 v[226:227], off
	s_mov_b32 m0, s66
	v_lshl_add_u64 v[228:229], s[64:65], 0, v[140:141]
	global_load_lds_dwordx4 v[228:229], off
	s_add_u32 s80, s62, 0x40000
	s_addc_u32 s81, s63, 0
	s_add_i32 s79, s76, s33
	s_mov_b32 m0, s79
	v_lshl_add_u64 v[240:241], s[80:81], 0, v[138:139]
	global_load_lds_dwordx4 v[240:241], off
	s_add_i32 m0, s79, 0x2000
	v_lshl_add_u64 v[240:241], s[80:81], 0, v[142:143]
	global_load_lds_dwordx4 v[240:241], off
	s_waitcnt vmcnt(8) lgkmcnt(0)
	s_barrier
	v_mfma_f32_16x16x32_bf16 v[60:63], v[152:155], v[174:177], 0
	v_mfma_f32_16x16x32_bf16 v[56:59], v[166:169], v[174:177], 0
	v_mfma_f32_16x16x32_bf16 v[52:55], v[152:155], v[182:185], 0
	v_mfma_f32_16x16x32_bf16 v[44:47], v[166:169], v[182:185], 0
	v_mfma_f32_16x16x32_bf16 v[36:39], v[152:155], v[190:193], 0
	v_mfma_f32_16x16x32_bf16 v[28:31], v[166:169], v[190:193], 0
	v_mfma_f32_16x16x32_bf16 v[20:23], v[152:155], v[198:201], 0
	v_mfma_f32_16x16x32_bf16 v[12:15], v[166:169], v[198:201], 0
	v_mfma_f32_16x16x32_bf16 v[60:63], v[162:165], v[178:181], v[60:63]
	v_mfma_f32_16x16x32_bf16 v[56:59], v[170:173], v[178:181], v[56:59]
	v_mfma_f32_16x16x32_bf16 v[52:55], v[162:165], v[186:189], v[52:55]
	v_mfma_f32_16x16x32_bf16 v[44:47], v[170:173], v[186:189], v[44:47]
	v_mfma_f32_16x16x32_bf16 v[36:39], v[162:165], v[194:197], v[36:39]
	v_mfma_f32_16x16x32_bf16 v[28:31], v[170:173], v[194:197], v[28:31]
	v_mfma_f32_16x16x32_bf16 v[20:23], v[162:165], v[202:205], v[20:23]
	v_mfma_f32_16x16x32_bf16 v[12:15], v[170:173], v[202:205], v[12:15]
	v_mfma_f32_16x16x32_bf16 v[48:51], v[206:209], v[174:177], 0
	v_mfma_f32_16x16x32_bf16 v[40:43], v[214:217], v[174:177], 0
	v_mfma_f32_16x16x32_bf16 v[32:35], v[206:209], v[182:185], 0
	v_mfma_f32_16x16x32_bf16 v[24:27], v[214:217], v[182:185], 0
	v_mfma_f32_16x16x32_bf16 v[16:19], v[206:209], v[190:193], 0
	v_mfma_f32_16x16x32_bf16 v[8:11], v[214:217], v[190:193], 0
	v_mfma_f32_16x16x32_bf16 v[4:7], v[206:209], v[198:201], 0
	v_mfma_f32_16x16x32_bf16 v[0:3], v[214:217], v[198:201], 0
	v_mfma_f32_16x16x32_bf16 v[48:51], v[210:213], v[178:181], v[48:51]
	v_mfma_f32_16x16x32_bf16 v[40:43], v[218:221], v[178:181], v[40:43]
	v_mfma_f32_16x16x32_bf16 v[32:35], v[210:213], v[186:189], v[32:35]
	v_mfma_f32_16x16x32_bf16 v[24:27], v[218:221], v[186:189], v[24:27]
	v_mfma_f32_16x16x32_bf16 v[16:19], v[210:213], v[194:197], v[16:19]
	v_mfma_f32_16x16x32_bf16 v[8:11], v[218:221], v[194:197], v[8:11]
	v_mfma_f32_16x16x32_bf16 v[4:7], v[210:213], v[202:205], v[4:7]
	v_mfma_f32_16x16x32_bf16 v[0:3], v[218:221], v[202:205], v[0:3]
	s_barrier
; #define PG8_STAGE(bufoff, gbase, voff) do { _Pragma("unroll") for (int _i = 0; _i < 2; ++_i) \
;         __builtin_amdgcn_global_load_lds((const unsigned*)((const char*)(gbase) + (voff)[_i]), (LAS unsigned*)(lds + (bufoff) + ldsw + _i * 8192), 16, 0, 0); } while (0)
; #define PG8_LDA(dst, b, h) do { _Pragma("unroll") for (int m = 0; m < 4; ++m) _Pragma("unroll") for (int k = 0; k < 2; ++k) dst[m][k] = *(const LAS bf16x8*)(lds + PG8_SA(b, h) + aoff + m * 2048 + k * 1024); } while (0)
; #define PG8_LDB(dst, b, h) do { _Pragma("unroll") for (int n = 0; n < 2; ++n) _Pragma("unroll") for (int k = 0; k < 2; ++k) dst[n][k] = *(const LAS bf16x8*)(lds + PG8_SB(b, h) + boff + n * 2048 + k * 1024); } while (0)
; #define PG8_MMA(ai, bj, At, Bt) do { __builtin_amdgcn_s_setprio(1); _Pragma("unroll") for (int m = 0; m < 4; ++m) _Pragma("unroll") for (int n = 0; n < 2; ++n) _Pragma("unroll") for (int k = 0; k < 2; ++k) \
;         acc[ai][bj][m][n] = __builtin_amdgcn_mfma_f32_16x16x32_bf16(Bt[n][k], At[m][k], acc[ai][bj][m][n], 0, 0, 0); __builtin_amdgcn_s_setprio(0); } while (0)
; #define PG8_WAIT_V(n) asm volatile("s_waitcnt vmcnt(" #n ")" ::: "memory")
; #define PG8_WAIT_L(n) asm volatile("s_waitcnt lgkmcnt(" #n ")" ::: "memory")
; #define PG8_BAR __builtin_amdgcn_s_barrier()
; #define PG8_SCHED __builtin_amdgcn_sched_barrier(0)
; template <class Epi>
; __device__ __forceinline__ void gemm_phase(LAS unsigned char* lds, const Gemm g, const StaticOrder& S, const Epi& E) {
;     ...
;             PG8_LDB(B0, 1, 0); PG8_SCHED; PG8_LDA(At, 1, 0); PG8_STAGE(PG8_SA(0, 1), a2 + hstepA, voffA);
;             PG8_WAIT_L(8); PG8_BAR; PG8_WAIT_L(0); PG8_MMA(0, 0, At, B0); PG8_BAR; PG8_SCHED;
;             PG8_LDB(B1, 1, 1); PG8_STAGE(PG8_SB(1, 0), b3, voffB);
;             PG8_BAR; PG8_WAIT_L(0); PG8_MMA(0, 1, At, B1); PG8_BAR;
;             PG8_LDA(At, 1, 1); PG8_STAGE(PG8_SA(1, 0), a3, voffA);
;             PG8_BAR; PG8_WAIT_L(0); PG8_MMA(1, 0, At, B0); PG8_BAR; PG8_SCHED;
;             PG8_STAGE(PG8_SB(1, 1), b3 + hstepB, voffB);
;             PG8_WAIT_V(6); PG8_BAR; PG8_MMA(1, 1, At, B1); PG8_BAR;
	s_add_i32 s79, 0, 0x18000
	v_add_u32_e32 v170, s79, v156
	ds_read_b128 v[152:155], v170
	ds_read_b128 v[162:165], v170 offset:1024
	ds_read_b128 v[166:169], v170 offset:2048
	ds_read_b128 v[170:173], v170 offset:3072
	ds_read_b128 v[174:177], v160 offset:32768
	ds_read_b128 v[178:181], v160 offset:33792
	ds_read_b128 v[182:185], v160 offset:34816
	ds_read_b128 v[186:189], v160 offset:35840
	ds_read_b128 v[190:193], v160 offset:36864
	ds_read_b128 v[194:197], v160 offset:37888
	ds_read_b128 v[198:201], v160 offset:38912
	ds_read_b128 v[202:205], v160 offset:39936
	s_add_i32 s98, 0, 0x1c000
	v_add_u32_e32 v218, s98, v156
	ds_read_b128 v[206:209], v218
	ds_read_b128 v[210:213], v218 offset:1024
	ds_read_b128 v[214:217], v218 offset:2048
	ds_read_b128 v[218:221], v218 offset:3072
	s_add_u32 s64, s64, 0x40000
	s_addc_u32 s65, s65, 0
	s_mov_b32 m0, s67
	v_lshl_add_u64 v[244:245], s[64:65], 0, v[136:137]
	global_load_lds_dwordx4 v[244:245], off
	s_mov_b32 m0, s68
	v_lshl_add_u64 v[244:245], s[64:65], 0, v[140:141]
	global_load_lds_dwordx4 v[244:245], off
	s_waitcnt vmcnt(8) lgkmcnt(0)
	s_barrier
	v_mfma_f32_16x16x32_bf16 v[124:127], v[152:155], v[174:177], v[124:127]
	v_mfma_f32_16x16x32_bf16 v[120:123], v[166:169], v[174:177], v[120:123]
	v_mfma_f32_16x16x32_bf16 v[116:119], v[152:155], v[182:185], v[116:119]
	v_mfma_f32_16x16x32_bf16 v[108:111], v[166:169], v[182:185], v[108:111]
	v_mfma_f32_16x16x32_bf16 v[100:103], v[152:155], v[190:193], v[100:103]
	v_mfma_f32_16x16x32_bf16 v[92:95], v[166:169], v[190:193], v[92:95]
	v_mfma_f32_16x16x32_bf16 v[84:87], v[152:155], v[198:201], v[84:87]
	v_mfma_f32_16x16x32_bf16 v[76:79], v[166:169], v[198:201], v[76:79]
	v_mfma_f32_16x16x32_bf16 v[124:127], v[162:165], v[178:181], v[124:127]
	v_mfma_f32_16x16x32_bf16 v[120:123], v[170:173], v[178:181], v[120:123]
	v_mfma_f32_16x16x32_bf16 v[116:119], v[162:165], v[186:189], v[116:119]
	v_mfma_f32_16x16x32_bf16 v[108:111], v[170:173], v[186:189], v[108:111]
	v_mfma_f32_16x16x32_bf16 v[100:103], v[162:165], v[194:197], v[100:103]
	v_mfma_f32_16x16x32_bf16 v[92:95], v[170:173], v[194:197], v[92:95]
	v_mfma_f32_16x16x32_bf16 v[84:87], v[162:165], v[202:205], v[84:87]
	v_mfma_f32_16x16x32_bf16 v[76:79], v[170:173], v[202:205], v[76:79]
	v_mfma_f32_16x16x32_bf16 v[112:115], v[206:209], v[174:177], v[112:115]
	v_mfma_f32_16x16x32_bf16 v[104:107], v[214:217], v[174:177], v[104:107]
	v_mfma_f32_16x16x32_bf16 v[96:99], v[206:209], v[182:185], v[96:99]
	v_mfma_f32_16x16x32_bf16 v[88:91], v[214:217], v[182:185], v[88:91]
	v_mfma_f32_16x16x32_bf16 v[80:83], v[206:209], v[190:193], v[80:83]
	v_mfma_f32_16x16x32_bf16 v[72:75], v[214:217], v[190:193], v[72:75]
	v_mfma_f32_16x16x32_bf16 v[68:71], v[206:209], v[198:201], v[68:71]
	v_mfma_f32_16x16x32_bf16 v[64:67], v[214:217], v[198:201], v[64:67]
	v_mfma_f32_16x16x32_bf16 v[112:115], v[210:213], v[178:181], v[112:115]
	v_mfma_f32_16x16x32_bf16 v[104:107], v[218:221], v[178:181], v[104:107]
	v_mfma_f32_16x16x32_bf16 v[96:99], v[210:213], v[186:189], v[96:99]
	v_mfma_f32_16x16x32_bf16 v[88:91], v[218:221], v[186:189], v[88:91]
	v_mfma_f32_16x16x32_bf16 v[80:83], v[210:213], v[194:197], v[80:83]
	v_mfma_f32_16x16x32_bf16 v[72:75], v[218:221], v[194:197], v[72:75]
	v_mfma_f32_16x16x32_bf16 v[68:71], v[210:213], v[202:205], v[68:71]
	v_mfma_f32_16x16x32_bf16 v[64:67], v[218:221], v[202:205], v[64:67]
	s_barrier
	ds_read_b128 v[174:177], v160 offset:49152
	ds_read_b128 v[178:181], v160 offset:50176
	ds_read_b128 v[182:185], v160 offset:51200
	ds_read_b128 v[186:189], v160 offset:52224
	ds_read_b128 v[190:193], v160 offset:53248
	ds_read_b128 v[194:197], v160 offset:54272
	ds_read_b128 v[198:201], v160 offset:55296
	ds_read_b128 v[202:205], v160 offset:56320
	s_add_i32 s65, s79, s33
	s_mov_b32 m0, s65
	v_lshl_add_u64 v[222:223], v[222:223], 0, s[28:29]
	global_load_lds_dwordx4 v[222:223], off
	s_add_i32 m0, s65, 0x2000
	v_lshl_add_u64 v[222:223], v[224:225], 0, s[28:29]
	global_load_lds_dwordx4 v[222:223], off
	s_mov_b32 m0, s71
	v_lshl_add_u64 v[222:223], v[226:227], 0, s[28:29]
	global_load_lds_dwordx4 v[222:223], off
	s_mov_b32 m0, s72
	v_lshl_add_u64 v[222:223], v[228:229], 0, s[28:29]
	global_load_lds_dwordx4 v[222:223], off
	s_add_u32 s62, s62, 0x40080
	s_addc_u32 s63, s63, 0
	s_add_i32 s64, s98, s33
	s_mov_b32 m0, s64
	v_lshl_add_u64 v[240:241], s[62:63], 0, v[138:139]
	global_load_lds_dwordx4 v[240:241], off
	s_add_i32 m0, s64, 0x2000
	v_lshl_add_u64 v[240:241], s[62:63], 0, v[142:143]
	global_load_lds_dwordx4 v[240:241], off
	s_waitcnt vmcnt(8) lgkmcnt(0)
	s_barrier
	v_mfma_f32_16x16x32_bf16 v[60:63], v[152:155], v[174:177], v[60:63]
	v_mfma_f32_16x16x32_bf16 v[56:59], v[166:169], v[174:177], v[56:59]
	v_mfma_f32_16x16x32_bf16 v[52:55], v[152:155], v[182:185], v[52:55]
	v_mfma_f32_16x16x32_bf16 v[44:47], v[166:169], v[182:185], v[44:47]
	v_mfma_f32_16x16x32_bf16 v[36:39], v[152:155], v[190:193], v[36:39]
	v_mfma_f32_16x16x32_bf16 v[28:31], v[166:169], v[190:193], v[28:31]
	v_mfma_f32_16x16x32_bf16 v[20:23], v[152:155], v[198:201], v[20:23]
	v_mfma_f32_16x16x32_bf16 v[12:15], v[166:169], v[198:201], v[12:15]
	v_mfma_f32_16x16x32_bf16 v[60:63], v[162:165], v[178:181], v[60:63]
	v_mfma_f32_16x16x32_bf16 v[56:59], v[170:173], v[178:181], v[56:59]
	v_mfma_f32_16x16x32_bf16 v[52:55], v[162:165], v[186:189], v[52:55]
	v_mfma_f32_16x16x32_bf16 v[44:47], v[170:173], v[186:189], v[44:47]
	v_mfma_f32_16x16x32_bf16 v[36:39], v[162:165], v[194:197], v[36:39]
	v_mfma_f32_16x16x32_bf16 v[28:31], v[170:173], v[194:197], v[28:31]
	v_mfma_f32_16x16x32_bf16 v[20:23], v[162:165], v[202:205], v[20:23]
	v_mfma_f32_16x16x32_bf16 v[12:15], v[170:173], v[202:205], v[12:15]
	v_mfma_f32_16x16x32_bf16 v[48:51], v[206:209], v[174:177], v[48:51]
	v_mfma_f32_16x16x32_bf16 v[40:43], v[214:217], v[174:177], v[40:43]
	v_mfma_f32_16x16x32_bf16 v[32:35], v[206:209], v[182:185], v[32:35]
	v_mfma_f32_16x16x32_bf16 v[24:27], v[214:217], v[182:185], v[24:27]
	v_mfma_f32_16x16x32_bf16 v[16:19], v[206:209], v[190:193], v[16:19]
	v_mfma_f32_16x16x32_bf16 v[8:11], v[214:217], v[190:193], v[8:11]
	v_mfma_f32_16x16x32_bf16 v[4:7], v[206:209], v[198:201], v[4:7]
	v_mfma_f32_16x16x32_bf16 v[0:3], v[214:217], v[198:201], v[0:3]
	v_mfma_f32_16x16x32_bf16 v[48:51], v[210:213], v[178:181], v[48:51]
	v_mfma_f32_16x16x32_bf16 v[40:43], v[218:221], v[178:181], v[40:43]
	v_mfma_f32_16x16x32_bf16 v[32:35], v[210:213], v[186:189], v[32:35]
	v_mfma_f32_16x16x32_bf16 v[24:27], v[218:221], v[186:189], v[24:27]
	v_mfma_f32_16x16x32_bf16 v[16:19], v[210:213], v[194:197], v[16:19]
	v_mfma_f32_16x16x32_bf16 v[8:11], v[218:221], v[194:197], v[8:11]
	v_mfma_f32_16x16x32_bf16 v[4:7], v[210:213], v[202:205], v[4:7]
	v_mfma_f32_16x16x32_bf16 v[0:3], v[218:221], v[202:205], v[0:3]
	s_add_i32 s78, s78, 2
	s_add_u32 s60, s60, 0x100
	s_addc_u32 s61, s61, 0
	s_add_u32 s37, s37, 0x100
	s_addc_u32 s39, s39, 0
	s_cmp_gt_u32 s78, 13
	s_barrier

; #define PG8_STAGE(bufoff, gbase, voff) do { _Pragma("unroll") for (int _i = 0; _i < 2; ++_i) \
;         __builtin_amdgcn_global_load_lds((const unsigned*)((const char*)(gbase) + (voff)[_i]), (LAS unsigned*)(lds + (bufoff) + ldsw + _i * 8192), 16, 0, 0); } while (0)
; #define PG8_LDA(dst, b, h) do { _Pragma("unroll") for (int m = 0; m < 4; ++m) _Pragma("unroll") for (int k = 0; k < 2; ++k) dst[m][k] = *(const LAS bf16x8*)(lds + PG8_SA(b, h) + aoff + m * 2048 + k * 1024); } while (0)
; #define PG8_LDB(dst, b, h) do { _Pragma("unroll") for (int n = 0; n < 2; ++n) _Pragma("unroll") for (int k = 0; k < 2; ++k) dst[n][k] = *(const LAS bf16x8*)(lds + PG8_SB(b, h) + boff + n * 2048 + k * 1024); } while (0)
; #define PG8_WAIT_L(n) asm volatile("s_waitcnt lgkmcnt(" #n ")" ::: "memory")
; #define PG8_BAR __builtin_amdgcn_s_barrier()
; #define PG8_SCHED __builtin_amdgcn_sched_barrier(0)
;     __device__ bool next(int i, Unit& u) const {
;         long L = (long)i * G + c;
;         if (L < nwg) {
;             int wgid = (int)L; { const int q = nwg / NXCD, r = nwg % NXCD, xcd = wgid % NXCD, off = wgid / NXCD; wgid = (xcd < r ? xcd * (q + 1) : r * (q + 1) + (xcd - r) * q) + off; }
;             const int nig = WGM * nN, gid = wgid / nig, fm = gid * WGM, gsz = (nM - fm) < WGM ? (nM - fm) : WGM;
;             u.pm = fm + ((wgid % nig) % gsz); u.pn = (wgid % nig) / gsz; u.kt0 = 0; u.nkt = nt; u.part = 0; return true;
;         }
;         L -= nwg; if (L >= (long)tail * nN * split) return false;
;         const int ks = (int)L % split, tu = (int)L / split, pairs = nt / 2, base = pairs / split, ex = pairs % split;
;         u.pm = nM + tu / nN; u.pn = tu % nN; u.kt0 = 2 * (ks * base + (ks < ex ? ks : ex)); u.nkt = 2 * (base + (ks < ex ? 1 : 0)); u.part = ks + 1; return true;
; template <class Epi>
; __device__ __forceinline__ void gemm_phase(LAS unsigned char* lds, const Gemm g, const StaticOrder& S, const Epi& E) {
;     ...
;             PG8_LDB(B0, 0, 0); PG8_SCHED; PG8_LDA(At, 0, 0); PG8_STAGE(PG8_SA(1, 1), a1 + hstepA, voffA);
;             PG8_WAIT_L(8); PG8_BAR; PG8_WAIT_L(0); PG8_MMA(0, 0, At, B0); PG8_BAR; PG8_SCHED;
;             PG8_LDB(B1, 0, 1); PG8_STAGE(PG8_SB(0, 0), b2, voffB);
.LBB0_896:
	ds_read_b128 v[150:153], v170
	ds_read_b128 v[154:157], v170 offset:1024
	ds_read_b128 v[174:177], v170 offset:2048
	ds_read_b128 v[178:181], v170 offset:3072
	ds_read_b128 v[182:185], v171
	ds_read_b128 v[186:189], v171 offset:1024
	ds_read_b128 v[190:193], v171 offset:2048
	ds_read_b128 v[194:197], v171 offset:3072
	ds_read_b128 v[198:201], v171 offset:4096
	ds_read_b128 v[202:205], v171 offset:5120
	ds_read_b128 v[206:209], v171 offset:6144
	ds_read_b128 v[210:213], v171 offset:7168
	ds_read_b128 v[214:217], v172
	ds_read_b128 v[218:221], v172 offset:1024
	ds_read_b128 v[222:225], v172 offset:2048
	ds_read_b128 v[226:229], v172 offset:3072
	s_add_i32 s73, s73, 1
	s_mul_i32 s0, s73, s62
	s_mul_hi_u32 s1, s73, s63
	s_add_i32 s1, s1, s0
	s_mul_i32 s0, s73, s63
	s_add_u32 s0, s0, s2
	s_addc_u32 s1, s1, s64
	v_cmp_gt_i64_e32 vcc, s[0:1], v[148:149]
	s_mov_b64 s[42:43], -1
	s_cbranch_vccz .LBB0_899
	s_and_b32 s45, s1, 0x7fffffff
	s_and_b32 s44, s0, 0xffffffe0
	s_mov_b64 s[42:43], 0
	s_cmp_lg_u64 s[44:45], 0x100
	s_mov_b64 s[44:45], 0
	s_cbranch_scc1 .LBB0_899
	s_and_b32 s1, s0, 3
	s_bfe_u32 s18, s0, 0x30002
	s_cmp_gt_u32 s18, 3
	v_sub_co_u32_e64 v0, s[40:41], s18, 4
	s_cselect_b32 s75, 0x41, 64
	s_and_b64 s[40:41], s[40:41], exec
	v_readfirstlane_b32 s40, v0
	s_cselect_b32 s74, s18, s40
	s_mul_i32 s18, s1, 5
	s_min_u32 s40, s1, 2
	s_add_i32 s40, s40, s18
	s_and_b32 s18, s0, 2
	s_lshl_b32 s40, s40, 1
	s_sub_i32 s76, 12, s18
	s_add_i32 s77, s1, 1
	s_mov_b64 s[44:45], -1

; #define PG8_STAGE(bufoff, gbase, voff) do { _Pragma("unroll") for (int _i = 0; _i < 2; ++_i) \
;         __builtin_amdgcn_global_load_lds((const unsigned*)((const char*)(gbase) + (voff)[_i]), (LAS unsigned*)(lds + (bufoff) + ldsw + _i * 8192), 16, 0, 0); } while (0)
; #define PG8_LDA(dst, b, h) do { _Pragma("unroll") for (int m = 0; m < 4; ++m) _Pragma("unroll") for (int k = 0; k < 2; ++k) dst[m][k] = *(const LAS bf16x8*)(lds + PG8_SA(b, h) + aoff + m * 2048 + k * 1024); } while (0)
; #define PG8_LDB(dst, b, h) do { _Pragma("unroll") for (int n = 0; n < 2; ++n) _Pragma("unroll") for (int k = 0; k < 2; ++k) dst[n][k] = *(const LAS bf16x8*)(lds + PG8_SB(b, h) + boff + n * 2048 + k * 1024); } while (0)
; #define PG8_WAIT_V(n) asm volatile("s_waitcnt vmcnt(" #n ")" ::: "memory")
; #define PG8_WAIT_L(n) asm volatile("s_waitcnt lgkmcnt(" #n ")" ::: "memory")
; #define PG8_BAR __builtin_amdgcn_s_barrier()
; #define PG8_SCHED __builtin_amdgcn_sched_barrier(0)
; template <class Epi>
; __device__ __forceinline__ void gemm_phase(LAS unsigned char* lds, const Gemm g, const StaticOrder& S, const Epi& E) {
;     ...
;         const char* nA = has_next ? (const char*)g.A + (size_t)nxt.pm * tstepA + (size_t)nxt.kt0 * kstep : cA; const char* nB = has_next ? (const char*)g.Bt + (size_t)nxt.pn * tstepB + (size_t)nxt.kt0 * kstep : cB;
;         const int nt = cur.nkt;
;         for (int t = 0; t < nt; t += 2) {
;             const bool last = (t == nt - 2);
;             const char* a1 = cA + (size_t)(t + 1) * kstep;
;             const char* a2 = last ? nA : cA + (size_t)(t + 2) * kstep; const char* b2 = last ? nB : cB + (size_t)(t + 2) * kstep;
;             const char* a3 = a2 + kstep; const char* b3 = b2 + kstep;
;             PG8_LDB(B0, 0, 0); PG8_SCHED; PG8_LDA(At, 0, 0); PG8_STAGE(PG8_SA(1, 1), a1 + hstepA, voffA);
;             PG8_WAIT_L(8); PG8_BAR; PG8_WAIT_L(0); PG8_MMA(0, 0, At, B0); PG8_BAR; PG8_SCHED;
;             PG8_LDB(B1, 0, 1); PG8_STAGE(PG8_SB(0, 0), b2, voffB);
;             PG8_BAR; PG8_WAIT_L(0); PG8_MMA(0, 1, At, B1); PG8_BAR;
;             PG8_LDA(At, 0, 1); PG8_STAGE(PG8_SA(0, 0), a2, voffA);
;             PG8_BAR; PG8_WAIT_L(0); PG8_MMA(1, 0, At, B0); PG8_BAR; PG8_SCHED;
;             PG8_STAGE(PG8_SB(0, 1), b2 + hstepB, voffB);
;             PG8_WAIT_V(6); PG8_BAR; PG8_MMA(1, 1, At, B1); PG8_BAR;
.LBB0_909:
	s_add_i32 s18, s81, -2
	s_add_u32 s46, s46, 0x160080
	s_addc_u32 s47, s47, 0
	s_add_u32 s41, s54, 0x100
	s_addc_u32 s82, s55, 0
	s_mov_b32 s54, 0
	s_add_i32 s83, s54, 2
	s_add_u32 s55, s46, 0xffea0080
	s_addc_u32 s56, s47, -1
	s_cmp_eq_u32 s18, s54
	s_cselect_b32 s54, s0, s41
	s_cselect_b32 s57, s45, s56
	s_cselect_b32 s56, s44, s55
	s_cselect_b32 s55, s1, s82
	s_add_i32 m0, s33, 0xc000
	v_lshl_add_u64 v[158:159], s[46:47], 0, v[144:145]
	global_load_lds_dwordx4 v[158:159], off
	s_add_i32 m0, s33, 0xe000
	v_lshl_add_u64 v[158:159], s[46:47], 0, v[146:147]
	global_load_lds_dwordx4 v[158:159], off
	s_waitcnt vmcnt(8) lgkmcnt(0)
	s_barrier
	v_mfma_f32_16x16x32_bf16 v[124:127], v[150:153], v[182:185], 0
	v_mfma_f32_16x16x32_bf16 v[120:123], v[174:177], v[182:185], 0
	v_mfma_f32_16x16x32_bf16 v[116:119], v[150:153], v[190:193], 0
	v_mfma_f32_16x16x32_bf16 v[108:111], v[174:177], v[190:193], 0
	v_mfma_f32_16x16x32_bf16 v[100:103], v[150:153], v[198:201], 0
	v_mfma_f32_16x16x32_bf16 v[92:95], v[174:177], v[198:201], 0
	v_mfma_f32_16x16x32_bf16 v[84:87], v[150:153], v[206:209], 0
	v_mfma_f32_16x16x32_bf16 v[76:79], v[174:177], v[206:209], 0
	v_mfma_f32_16x16x32_bf16 v[124:127], v[154:157], v[186:189], v[124:127]
	v_mfma_f32_16x16x32_bf16 v[120:123], v[178:181], v[186:189], v[120:123]
	v_mfma_f32_16x16x32_bf16 v[116:119], v[154:157], v[194:197], v[116:119]
	v_mfma_f32_16x16x32_bf16 v[108:111], v[178:181], v[194:197], v[108:111]
	v_mfma_f32_16x16x32_bf16 v[100:103], v[154:157], v[202:205], v[100:103]
	v_mfma_f32_16x16x32_bf16 v[92:95], v[178:181], v[202:205], v[92:95]
	v_mfma_f32_16x16x32_bf16 v[84:87], v[154:157], v[210:213], v[84:87]
	v_mfma_f32_16x16x32_bf16 v[76:79], v[178:181], v[210:213], v[76:79]
	v_mfma_f32_16x16x32_bf16 v[112:115], v[214:217], v[182:185], 0
	v_mfma_f32_16x16x32_bf16 v[104:107], v[222:225], v[182:185], 0
	v_mfma_f32_16x16x32_bf16 v[96:99], v[214:217], v[190:193], 0
	v_mfma_f32_16x16x32_bf16 v[88:91], v[222:225], v[190:193], 0
	v_mfma_f32_16x16x32_bf16 v[80:83], v[214:217], v[198:201], 0
	v_mfma_f32_16x16x32_bf16 v[72:75], v[222:225], v[198:201], 0
	v_mfma_f32_16x16x32_bf16 v[68:71], v[214:217], v[206:209], 0
	v_mfma_f32_16x16x32_bf16 v[64:67], v[222:225], v[206:209], 0
	v_mfma_f32_16x16x32_bf16 v[112:115], v[218:221], v[186:189], v[112:115]
	v_mfma_f32_16x16x32_bf16 v[104:107], v[226:229], v[186:189], v[104:107]
	v_mfma_f32_16x16x32_bf16 v[96:99], v[218:221], v[194:197], v[96:99]
	v_mfma_f32_16x16x32_bf16 v[88:91], v[226:229], v[194:197], v[88:91]
	v_mfma_f32_16x16x32_bf16 v[80:83], v[218:221], v[202:205], v[80:83]
	v_mfma_f32_16x16x32_bf16 v[72:75], v[226:229], v[202:205], v[72:75]
	v_mfma_f32_16x16x32_bf16 v[68:71], v[218:221], v[210:213], v[68:71]
	v_mfma_f32_16x16x32_bf16 v[64:67], v[226:229], v[210:213], v[64:67]
	s_barrier
	ds_read_b128 v[182:185], v171 offset:16384
	ds_read_b128 v[186:189], v171 offset:17408
	ds_read_b128 v[190:193], v171 offset:18432
	ds_read_b128 v[194:197], v171 offset:19456
	ds_read_b128 v[198:201], v171 offset:20480
	ds_read_b128 v[202:205], v171 offset:21504
	ds_read_b128 v[206:209], v171 offset:22528
	ds_read_b128 v[210:213], v171 offset:23552
	s_add_i32 s84, s65, s21
	s_mov_b32 m0, s84
	v_lshl_add_u64 v[158:159], s[54:55], 0, v[138:139]
	global_load_lds_dwordx4 v[158:159], off
	s_add_i32 m0, s84, 0x2000
	v_lshl_add_u64 v[230:231], s[54:55], 0, v[142:143]
	global_load_lds_dwordx4 v[230:231], off
	s_mov_b32 m0, s33
	v_lshl_add_u64 v[232:233], s[56:57], 0, v[136:137]
	global_load_lds_dwordx4 v[232:233], off
	s_mov_b32 m0, s35
	v_lshl_add_u64 v[234:235], s[56:57], 0, v[140:141]
	global_load_lds_dwordx4 v[234:235], off
	s_add_u32 s84, s54, 0xb0000
	s_addc_u32 s85, s55, 0
	s_add_i32 s86, s66, s21
	s_mov_b32 m0, s86
	v_lshl_add_u64 v[240:241], s[84:85], 0, v[138:139]
	global_load_lds_dwordx4 v[240:241], off
	s_add_i32 m0, s86, 0x2000
	v_lshl_add_u64 v[240:241], s[84:85], 0, v[142:143]
	global_load_lds_dwordx4 v[240:241], off
	s_waitcnt vmcnt(8) lgkmcnt(0)
	s_barrier
	v_mfma_f32_16x16x32_bf16 v[60:63], v[150:153], v[182:185], 0
	v_mfma_f32_16x16x32_bf16 v[56:59], v[174:177], v[182:185], 0
	v_mfma_f32_16x16x32_bf16 v[52:55], v[150:153], v[190:193], 0
	v_mfma_f32_16x16x32_bf16 v[44:47], v[174:177], v[190:193], 0
	v_mfma_f32_16x16x32_bf16 v[36:39], v[150:153], v[198:201], 0
	v_mfma_f32_16x16x32_bf16 v[28:31], v[174:177], v[198:201], 0
	v_mfma_f32_16x16x32_bf16 v[20:23], v[150:153], v[206:209], 0
	v_mfma_f32_16x16x32_bf16 v[12:15], v[174:177], v[206:209], 0
	v_mfma_f32_16x16x32_bf16 v[60:63], v[154:157], v[186:189], v[60:63]
	v_mfma_f32_16x16x32_bf16 v[56:59], v[178:181], v[186:189], v[56:59]
	v_mfma_f32_16x16x32_bf16 v[52:55], v[154:157], v[194:197], v[52:55]
	v_mfma_f32_16x16x32_bf16 v[44:47], v[178:181], v[194:197], v[44:47]
	v_mfma_f32_16x16x32_bf16 v[36:39], v[154:157], v[202:205], v[36:39]
	v_mfma_f32_16x16x32_bf16 v[28:31], v[178:181], v[202:205], v[28:31]
	v_mfma_f32_16x16x32_bf16 v[20:23], v[154:157], v[210:213], v[20:23]
	v_mfma_f32_16x16x32_bf16 v[12:15], v[178:181], v[210:213], v[12:15]
	v_mfma_f32_16x16x32_bf16 v[48:51], v[214:217], v[182:185], 0
	v_mfma_f32_16x16x32_bf16 v[40:43], v[222:225], v[182:185], 0
	v_mfma_f32_16x16x32_bf16 v[32:35], v[214:217], v[190:193], 0
	v_mfma_f32_16x16x32_bf16 v[24:27], v[222:225], v[190:193], 0
	v_mfma_f32_16x16x32_bf16 v[16:19], v[214:217], v[198:201], 0
	v_mfma_f32_16x16x32_bf16 v[8:11], v[222:225], v[198:201], 0
	v_mfma_f32_16x16x32_bf16 v[4:7], v[214:217], v[206:209], 0
	v_mfma_f32_16x16x32_bf16 v[0:3], v[222:225], v[206:209], 0
	v_mfma_f32_16x16x32_bf16 v[48:51], v[218:221], v[186:189], v[48:51]
	v_mfma_f32_16x16x32_bf16 v[40:43], v[226:229], v[186:189], v[40:43]
	v_mfma_f32_16x16x32_bf16 v[32:35], v[218:221], v[194:197], v[32:35]
	v_mfma_f32_16x16x32_bf16 v[24:27], v[226:229], v[194:197], v[24:27]
	v_mfma_f32_16x16x32_bf16 v[16:19], v[218:221], v[202:205], v[16:19]
	v_mfma_f32_16x16x32_bf16 v[8:11], v[226:229], v[202:205], v[8:11]
	v_mfma_f32_16x16x32_bf16 v[4:7], v[218:221], v[210:213], v[4:7]
	v_mfma_f32_16x16x32_bf16 v[0:3], v[226:229], v[210:213], v[0:3]
	s_barrier
; #define PG8_STAGE(bufoff, gbase, voff) do { _Pragma("unroll") for (int _i = 0; _i < 2; ++_i) \
;         __builtin_amdgcn_global_load_lds((const unsigned*)((const char*)(gbase) + (voff)[_i]), (LAS unsigned*)(lds + (bufoff) + ldsw + _i * 8192), 16, 0, 0); } while (0)
; #define PG8_LDA(dst, b, h) do { _Pragma("unroll") for (int m = 0; m < 4; ++m) _Pragma("unroll") for (int k = 0; k < 2; ++k) dst[m][k] = *(const LAS bf16x8*)(lds + PG8_SA(b, h) + aoff + m * 2048 + k * 1024); } while (0)
; #define PG8_LDB(dst, b, h) do { _Pragma("unroll") for (int n = 0; n < 2; ++n) _Pragma("unroll") for (int k = 0; k < 2; ++k) dst[n][k] = *(const LAS bf16x8*)(lds + PG8_SB(b, h) + boff + n * 2048 + k * 1024); } while (0)
; #define PG8_MMA(ai, bj, At, Bt) do { __builtin_amdgcn_s_setprio(1); _Pragma("unroll") for (int m = 0; m < 4; ++m) _Pragma("unroll") for (int n = 0; n < 2; ++n) _Pragma("unroll") for (int k = 0; k < 2; ++k) \
;         acc[ai][bj][m][n] = __builtin_amdgcn_mfma_f32_16x16x32_bf16(Bt[n][k], At[m][k], acc[ai][bj][m][n], 0, 0, 0); __builtin_amdgcn_s_setprio(0); } while (0)
; #define PG8_WAIT_V(n) asm volatile("s_waitcnt vmcnt(" #n ")" ::: "memory")
; #define PG8_WAIT_L(n) asm volatile("s_waitcnt lgkmcnt(" #n ")" ::: "memory")
; #define PG8_BAR __builtin_amdgcn_s_barrier()
; #define PG8_SCHED __builtin_amdgcn_sched_barrier(0)
; template <class Epi>
; __device__ __forceinline__ void gemm_phase(LAS unsigned char* lds, const Gemm g, const StaticOrder& S, const Epi& E) {
;     ...
;             PG8_LDB(B0, 1, 0); PG8_SCHED; PG8_LDA(At, 1, 0); PG8_STAGE(PG8_SA(0, 1), a2 + hstepA, voffA);
;             PG8_WAIT_L(8); PG8_BAR; PG8_WAIT_L(0); PG8_MMA(0, 0, At, B0); PG8_BAR; PG8_SCHED;
;             PG8_LDB(B1, 1, 1); PG8_STAGE(PG8_SB(1, 0), b3, voffB);
;             PG8_BAR; PG8_WAIT_L(0); PG8_MMA(0, 1, At, B1); PG8_BAR;
;             PG8_LDA(At, 1, 1); PG8_STAGE(PG8_SA(1, 0), a3, voffA);
;             PG8_BAR; PG8_WAIT_L(0); PG8_MMA(1, 0, At, B0); PG8_BAR; PG8_SCHED;
;             PG8_STAGE(PG8_SB(1, 1), b3 + hstepB, voffB);
;             PG8_WAIT_V(6); PG8_BAR; PG8_MMA(1, 1, At, B1); PG8_BAR;
	s_add_i32 s84, 0, 0x18000
	v_add_u32_e32 v173, s84, v168
	ds_read_b128 v[150:153], v173
	ds_read_b128 v[154:157], v173 offset:1024
	ds_read_b128 v[174:177], v173 offset:2048
	ds_read_b128 v[178:181], v173 offset:3072
	ds_read_b128 v[182:185], v171 offset:32768
	ds_read_b128 v[186:189], v171 offset:33792
	ds_read_b128 v[190:193], v171 offset:34816
	ds_read_b128 v[194:197], v171 offset:35840
	ds_read_b128 v[198:201], v171 offset:36864
	ds_read_b128 v[202:205], v171 offset:37888
	ds_read_b128 v[206:209], v171 offset:38912
	ds_read_b128 v[210:213], v171 offset:39936
	s_add_i32 s98, 0, 0x1c000
	v_add_u32_e32 v246, s98, v168
	ds_read_b128 v[214:217], v246
	ds_read_b128 v[218:221], v246 offset:1024
	ds_read_b128 v[222:225], v246 offset:2048
	ds_read_b128 v[226:229], v246 offset:3072
	s_add_u32 s56, s56, 0x160000
	s_addc_u32 s57, s57, 0
	s_mov_b32 m0, s58
	v_lshl_add_u64 v[244:245], s[56:57], 0, v[136:137]
	global_load_lds_dwordx4 v[244:245], off
	s_mov_b32 m0, s59
	v_lshl_add_u64 v[244:245], s[56:57], 0, v[140:141]
	global_load_lds_dwordx4 v[244:245], off
	s_waitcnt vmcnt(8) lgkmcnt(0)
	s_barrier
	v_mfma_f32_16x16x32_bf16 v[124:127], v[150:153], v[182:185], v[124:127]
	v_mfma_f32_16x16x32_bf16 v[120:123], v[174:177], v[182:185], v[120:123]
	v_mfma_f32_16x16x32_bf16 v[116:119], v[150:153], v[190:193], v[116:119]
	v_mfma_f32_16x16x32_bf16 v[108:111], v[174:177], v[190:193], v[108:111]
	v_mfma_f32_16x16x32_bf16 v[100:103], v[150:153], v[198:201], v[100:103]
	v_mfma_f32_16x16x32_bf16 v[92:95], v[174:177], v[198:201], v[92:95]
	v_mfma_f32_16x16x32_bf16 v[84:87], v[150:153], v[206:209], v[84:87]
	v_mfma_f32_16x16x32_bf16 v[76:79], v[174:177], v[206:209], v[76:79]
	v_mfma_f32_16x16x32_bf16 v[124:127], v[154:157], v[186:189], v[124:127]
	v_mfma_f32_16x16x32_bf16 v[120:123], v[178:181], v[186:189], v[120:123]
	v_mfma_f32_16x16x32_bf16 v[116:119], v[154:157], v[194:197], v[116:119]
	v_mfma_f32_16x16x32_bf16 v[108:111], v[178:181], v[194:197], v[108:111]
	v_mfma_f32_16x16x32_bf16 v[100:103], v[154:157], v[202:205], v[100:103]
	v_mfma_f32_16x16x32_bf16 v[92:95], v[178:181], v[202:205], v[92:95]
	v_mfma_f32_16x16x32_bf16 v[84:87], v[154:157], v[210:213], v[84:87]
	v_mfma_f32_16x16x32_bf16 v[76:79], v[178:181], v[210:213], v[76:79]
	v_mfma_f32_16x16x32_bf16 v[112:115], v[214:217], v[182:185], v[112:115]
	v_mfma_f32_16x16x32_bf16 v[104:107], v[222:225], v[182:185], v[104:107]
	v_mfma_f32_16x16x32_bf16 v[96:99], v[214:217], v[190:193], v[96:99]
	v_mfma_f32_16x16x32_bf16 v[88:91], v[222:225], v[190:193], v[88:91]
	v_mfma_f32_16x16x32_bf16 v[80:83], v[214:217], v[198:201], v[80:83]
	v_mfma_f32_16x16x32_bf16 v[72:75], v[222:225], v[198:201], v[72:75]
	v_mfma_f32_16x16x32_bf16 v[68:71], v[214:217], v[206:209], v[68:71]
	v_mfma_f32_16x16x32_bf16 v[64:67], v[222:225], v[206:209], v[64:67]
	v_mfma_f32_16x16x32_bf16 v[112:115], v[218:221], v[186:189], v[112:115]
	v_mfma_f32_16x16x32_bf16 v[104:107], v[226:229], v[186:189], v[104:107]
	v_mfma_f32_16x16x32_bf16 v[96:99], v[218:221], v[194:197], v[96:99]
	v_mfma_f32_16x16x32_bf16 v[88:91], v[226:229], v[194:197], v[88:91]
	v_mfma_f32_16x16x32_bf16 v[80:83], v[218:221], v[202:205], v[80:83]
	v_mfma_f32_16x16x32_bf16 v[72:75], v[226:229], v[202:205], v[72:75]
	v_mfma_f32_16x16x32_bf16 v[68:71], v[218:221], v[210:213], v[68:71]
	v_mfma_f32_16x16x32_bf16 v[64:67], v[226:229], v[210:213], v[64:67]
	s_barrier
	ds_read_b128 v[182:185], v171 offset:49152
	ds_read_b128 v[186:189], v171 offset:50176
	ds_read_b128 v[190:193], v171 offset:51200
	ds_read_b128 v[194:197], v171 offset:52224
	ds_read_b128 v[198:201], v171 offset:53248
	ds_read_b128 v[202:205], v171 offset:54272
	ds_read_b128 v[206:209], v171 offset:55296
	ds_read_b128 v[210:213], v171 offset:56320
	s_add_i32 s57, s84, s21
	s_mov_b32 m0, s57
	v_lshl_add_u64 v[158:159], v[158:159], 0, s[22:23]
	global_load_lds_dwordx4 v[158:159], off
	s_add_i32 m0, s57, 0x2000
	v_lshl_add_u64 v[158:159], v[230:231], 0, s[22:23]
	global_load_lds_dwordx4 v[158:159], off
	s_mov_b32 m0, s60
	v_lshl_add_u64 v[158:159], v[232:233], 0, s[22:23]
	global_load_lds_dwordx4 v[158:159], off
	s_mov_b32 m0, s61
	v_lshl_add_u64 v[158:159], v[234:235], 0, s[22:23]
	global_load_lds_dwordx4 v[158:159], off
	s_add_u32 s54, s54, 0xb0080
	s_addc_u32 s55, s55, 0
	s_add_i32 s56, s98, s21
	s_mov_b32 m0, s56
	v_lshl_add_u64 v[240:241], s[54:55], 0, v[138:139]
	global_load_lds_dwordx4 v[240:241], off
	s_add_i32 m0, s56, 0x2000
	v_lshl_add_u64 v[240:241], s[54:55], 0, v[142:143]
	global_load_lds_dwordx4 v[240:241], off
	s_waitcnt vmcnt(8) lgkmcnt(0)
	s_barrier
	v_mfma_f32_16x16x32_bf16 v[60:63], v[150:153], v[182:185], v[60:63]
	v_mfma_f32_16x16x32_bf16 v[56:59], v[174:177], v[182:185], v[56:59]
	v_mfma_f32_16x16x32_bf16 v[52:55], v[150:153], v[190:193], v[52:55]
	v_mfma_f32_16x16x32_bf16 v[44:47], v[174:177], v[190:193], v[44:47]
	v_mfma_f32_16x16x32_bf16 v[36:39], v[150:153], v[198:201], v[36:39]
	v_mfma_f32_16x16x32_bf16 v[28:31], v[174:177], v[198:201], v[28:31]
	v_mfma_f32_16x16x32_bf16 v[20:23], v[150:153], v[206:209], v[20:23]
	v_mfma_f32_16x16x32_bf16 v[12:15], v[174:177], v[206:209], v[12:15]
	v_mfma_f32_16x16x32_bf16 v[60:63], v[154:157], v[186:189], v[60:63]
	v_mfma_f32_16x16x32_bf16 v[56:59], v[178:181], v[186:189], v[56:59]
	v_mfma_f32_16x16x32_bf16 v[52:55], v[154:157], v[194:197], v[52:55]
	v_mfma_f32_16x16x32_bf16 v[44:47], v[178:181], v[194:197], v[44:47]
	v_mfma_f32_16x16x32_bf16 v[36:39], v[154:157], v[202:205], v[36:39]
	v_mfma_f32_16x16x32_bf16 v[28:31], v[178:181], v[202:205], v[28:31]
	v_mfma_f32_16x16x32_bf16 v[20:23], v[154:157], v[210:213], v[20:23]
	v_mfma_f32_16x16x32_bf16 v[12:15], v[178:181], v[210:213], v[12:15]
	v_mfma_f32_16x16x32_bf16 v[48:51], v[214:217], v[182:185], v[48:51]
	v_mfma_f32_16x16x32_bf16 v[40:43], v[222:225], v[182:185], v[40:43]
	v_mfma_f32_16x16x32_bf16 v[32:35], v[214:217], v[190:193], v[32:35]
	v_mfma_f32_16x16x32_bf16 v[24:27], v[222:225], v[190:193], v[24:27]
	v_mfma_f32_16x16x32_bf16 v[16:19], v[214:217], v[198:201], v[16:19]
	v_mfma_f32_16x16x32_bf16 v[8:11], v[222:225], v[198:201], v[8:11]
	v_mfma_f32_16x16x32_bf16 v[4:7], v[214:217], v[206:209], v[4:7]
	v_mfma_f32_16x16x32_bf16 v[0:3], v[222:225], v[206:209], v[0:3]
	v_mfma_f32_16x16x32_bf16 v[48:51], v[218:221], v[186:189], v[48:51]
	v_mfma_f32_16x16x32_bf16 v[40:43], v[226:229], v[186:189], v[40:43]
	v_mfma_f32_16x16x32_bf16 v[32:35], v[218:221], v[194:197], v[32:35]
	v_mfma_f32_16x16x32_bf16 v[24:27], v[226:229], v[194:197], v[24:27]
	v_mfma_f32_16x16x32_bf16 v[16:19], v[218:221], v[202:205], v[16:19]
	v_mfma_f32_16x16x32_bf16 v[8:11], v[226:229], v[202:205], v[8:11]
	v_mfma_f32_16x16x32_bf16 v[4:7], v[218:221], v[210:213], v[4:7]
	v_mfma_f32_16x16x32_bf16 v[0:3], v[226:229], v[210:213], v[0:3]
	s_add_u32 s46, s46, 0x100
	s_addc_u32 s47, s47, 0
	s_add_u32 s41, s41, 0x100
	s_addc_u32 s82, s82, 0
	s_cmp_ge_i32 s83, s81
	s_mov_b32 s54, s83
	s_barrier

; #define PG8_STAGE(bufoff, gbase, voff) do { _Pragma("unroll") for (int _i = 0; _i < 2; ++_i) \
;         __builtin_amdgcn_global_load_lds((const unsigned*)((const char*)(gbase) + (voff)[_i]), (LAS unsigned*)(lds + (bufoff) + ldsw + _i * 8192), 16, 0, 0); } while (0)
; #define PG8_LDA(dst, b, h) do { _Pragma("unroll") for (int m = 0; m < 4; ++m) _Pragma("unroll") for (int k = 0; k < 2; ++k) dst[m][k] = *(const LAS bf16x8*)(lds + PG8_SA(b, h) + aoff + m * 2048 + k * 1024); } while (0)
; #define PG8_LDB(dst, b, h) do { _Pragma("unroll") for (int n = 0; n < 2; ++n) _Pragma("unroll") for (int k = 0; k < 2; ++k) dst[n][k] = *(const LAS bf16x8*)(lds + PG8_SB(b, h) + boff + n * 2048 + k * 1024); } while (0)
; #define PG8_WAIT_L(n) asm volatile("s_waitcnt lgkmcnt(" #n ")" ::: "memory")
; #define PG8_BAR __builtin_amdgcn_s_barrier()
; #define PG8_SCHED __builtin_amdgcn_sched_barrier(0)
;     __device__ bool next(int i, Unit& u) const {
;         long L = (long)i * G + c;
;         if (L < nwg) {
;             int wgid = (int)L; { const int q = nwg / NXCD, r = nwg % NXCD, xcd = wgid % NXCD, off = wgid / NXCD; wgid = (xcd < r ? xcd * (q + 1) : r * (q + 1) + (xcd - r) * q) + off; }
;             const int nig = WGM * nN, gid = wgid / nig, fm = gid * WGM, gsz = (nM - fm) < WGM ? (nM - fm) : WGM;
;             u.pm = fm + ((wgid % nig) % gsz); u.pn = (wgid % nig) / gsz; u.kt0 = 0; u.nkt = nt; u.part = 0; return true;
;         }
;         L -= nwg; if (L >= (long)tail * nN * split) return false;
;         const int ks = (int)L % split, tu = (int)L / split, pairs = nt / 2, base = pairs / split, ex = pairs % split;
;         u.pm = nM + tu / nN; u.pn = tu % nN; u.kt0 = 2 * (ks * base + (ks < ex ? ks : ex)); u.nkt = 2 * (base + (ks < ex ? 1 : 0)); u.part = ks + 1; return true;
; template <class Epi>
; __device__ __forceinline__ void gemm_phase(LAS unsigned char* lds, const Gemm g, const StaticOrder& S, const Epi& E) {
;     ...
;             PG8_LDB(B0, 0, 0); PG8_SCHED; PG8_LDA(At, 0, 0); PG8_STAGE(PG8_SA(1, 1), a1 + hstepA, voffA);
;             PG8_WAIT_L(8); PG8_BAR; PG8_WAIT_L(0); PG8_MMA(0, 0, At, B0); PG8_BAR; PG8_SCHED;
;             PG8_LDB(B1, 0, 1); PG8_STAGE(PG8_SB(0, 0), b2, voffB);
.LBB0_1132:
	ds_read_b128 v[150:153], v129
	ds_read_b128 v[154:157], v129 offset:1024
	ds_read_b128 v[158:161], v129 offset:2048
	ds_read_b128 v[166:169], v129 offset:3072
	ds_read_b128 v[170:173], v163
	ds_read_b128 v[174:177], v163 offset:1024
	ds_read_b128 v[178:181], v163 offset:2048
	ds_read_b128 v[182:185], v163 offset:3072
	ds_read_b128 v[186:189], v163 offset:4096
	ds_read_b128 v[190:193], v163 offset:5120
	ds_read_b128 v[194:197], v163 offset:6144
	ds_read_b128 v[198:201], v163 offset:7168
	ds_read_b128 v[202:205], v164
	ds_read_b128 v[206:209], v164 offset:1024
	ds_read_b128 v[210:213], v164 offset:2048
	ds_read_b128 v[214:217], v164 offset:3072
	s_add_i32 s72, s72, 1
	s_mul_i32 s0, s72, s62
	s_mul_hi_u32 s1, s72, s63
	s_add_i32 s1, s1, s0
	s_mul_i32 s0, s72, s63
	s_add_u32 s0, s0, s2
	s_addc_u32 s1, s1, s65
	v_cmp_gt_i64_e32 vcc, s[0:1], v[148:149]
	s_mov_b64 s[46:47], -1
	s_cbranch_vccz .LBB0_1135
	s_and_b32 s49, s1, 0x7fffffff
	s_and_b32 s48, s0, 0xffffffe0
	s_mov_b64 s[46:47], 0
	s_cmp_lg_u64 s[48:49], 0x100
	s_mov_b64 s[48:49], 0
	s_cbranch_scc1 .LBB0_1135
	s_and_b32 s1, s0, 3
	s_bfe_u32 s41, s0, 0x30002
	s_cmp_gt_u32 s41, 3
	v_sub_co_u32_e64 v0, s[38:39], s41, 4
	s_cselect_b32 s40, 0x41, 64
	s_and_b64 s[38:39], s[38:39], exec
	v_readfirstlane_b32 s38, v0
	s_mov_b32 s73, 4
	s_cselect_b32 s42, s41, s38
	s_lshl_b32 s38, s1, 2
	s_add_i32 s74, s1, 1
	s_mov_b64 s[48:49], -1

; #define PG8_STAGE(bufoff, gbase, voff) do { _Pragma("unroll") for (int _i = 0; _i < 2; ++_i) \
;         __builtin_amdgcn_global_load_lds((const unsigned*)((const char*)(gbase) + (voff)[_i]), (LAS unsigned*)(lds + (bufoff) + ldsw + _i * 8192), 16, 0, 0); } while (0)
; #define PG8_LDA(dst, b, h) do { _Pragma("unroll") for (int m = 0; m < 4; ++m) _Pragma("unroll") for (int k = 0; k < 2; ++k) dst[m][k] = *(const LAS bf16x8*)(lds + PG8_SA(b, h) + aoff + m * 2048 + k * 1024); } while (0)
; #define PG8_LDB(dst, b, h) do { _Pragma("unroll") for (int n = 0; n < 2; ++n) _Pragma("unroll") for (int k = 0; k < 2; ++k) dst[n][k] = *(const LAS bf16x8*)(lds + PG8_SB(b, h) + boff + n * 2048 + k * 1024); } while (0)
; #define PG8_WAIT_V(n) asm volatile("s_waitcnt vmcnt(" #n ")" ::: "memory")
; #define PG8_WAIT_L(n) asm volatile("s_waitcnt lgkmcnt(" #n ")" ::: "memory")
; #define PG8_BAR __builtin_amdgcn_s_barrier()
; #define PG8_SCHED __builtin_amdgcn_sched_barrier(0)
; template <class Epi>
; __device__ __forceinline__ void gemm_phase(LAS unsigned char* lds, const Gemm g, const StaticOrder& S, const Epi& E) {
;     ...
;         const char* nA = has_next ? (const char*)g.A + (size_t)nxt.pm * tstepA + (size_t)nxt.kt0 * kstep : cA; const char* nB = has_next ? (const char*)g.Bt + (size_t)nxt.pn * tstepB + (size_t)nxt.kt0 * kstep : cB;
;         const int nt = cur.nkt;
;         for (int t = 0; t < nt; t += 2) {
;             const bool last = (t == nt - 2);
;             const char* a1 = cA + (size_t)(t + 1) * kstep;
;             const char* a2 = last ? nA : cA + (size_t)(t + 2) * kstep; const char* b2 = last ? nB : cB + (size_t)(t + 2) * kstep;
;             const char* a3 = a2 + kstep; const char* b3 = b2 + kstep;
;             PG8_LDB(B0, 0, 0); PG8_SCHED; PG8_LDA(At, 0, 0); PG8_STAGE(PG8_SA(1, 1), a1 + hstepA, voffA);
;             PG8_WAIT_L(8); PG8_BAR; PG8_WAIT_L(0); PG8_MMA(0, 0, At, B0); PG8_BAR; PG8_SCHED;
;             PG8_LDB(B1, 0, 1); PG8_STAGE(PG8_SB(0, 0), b2, voffB);
;             PG8_BAR; PG8_WAIT_L(0); PG8_MMA(0, 1, At, B1); PG8_BAR;
;             PG8_LDA(At, 0, 1); PG8_STAGE(PG8_SA(0, 0), a2, voffA);
;             PG8_BAR; PG8_WAIT_L(0); PG8_MMA(1, 0, At, B0); PG8_BAR; PG8_SCHED;
;             PG8_STAGE(PG8_SB(0, 1), b2 + hstepB, voffB);
;             PG8_WAIT_V(6); PG8_BAR; PG8_MMA(1, 1, At, B1); PG8_BAR;
.LBB0_1145:
	s_add_i32 s39, s76, -2
	s_add_u32 s50, s50, 0x40080
	s_addc_u32 s51, s51, 0
	s_add_u32 s41, s54, 0x100
	s_addc_u32 s43, s55, 0
	s_mov_b32 s45, 0
	s_add_i32 s77, s45, 2
	s_add_u32 s54, s50, 0xfffc0080
	s_addc_u32 s55, s51, -1
	s_cmp_eq_u32 s39, s45
	s_cselect_b32 s57, s49, s55
	s_cselect_b32 s56, s48, s54
	s_cselect_b32 s55, s1, s43
	s_cselect_b32 s54, s0, s41
	s_add_i32 m0, s33, 0xc000
	v_lshl_add_u64 v[242:243], s[50:51], 0, v[144:145]
	global_load_lds_dwordx4 v[242:243], off
	s_add_i32 m0, s33, 0xe000
	v_lshl_add_u64 v[242:243], s[50:51], 0, v[146:147]
	global_load_lds_dwordx4 v[242:243], off
	s_waitcnt vmcnt(8) lgkmcnt(0)
	s_barrier
	v_mfma_f32_16x16x32_bf16 v[124:127], v[150:153], v[170:173], 0
	v_mfma_f32_16x16x32_bf16 v[120:123], v[158:161], v[170:173], 0
	v_mfma_f32_16x16x32_bf16 v[116:119], v[150:153], v[178:181], 0
	v_mfma_f32_16x16x32_bf16 v[108:111], v[158:161], v[178:181], 0
	v_mfma_f32_16x16x32_bf16 v[100:103], v[150:153], v[186:189], 0
	v_mfma_f32_16x16x32_bf16 v[92:95], v[158:161], v[186:189], 0
	v_mfma_f32_16x16x32_bf16 v[84:87], v[150:153], v[194:197], 0
	v_mfma_f32_16x16x32_bf16 v[76:79], v[158:161], v[194:197], 0
	v_mfma_f32_16x16x32_bf16 v[124:127], v[154:157], v[174:177], v[124:127]
	v_mfma_f32_16x16x32_bf16 v[120:123], v[166:169], v[174:177], v[120:123]
	v_mfma_f32_16x16x32_bf16 v[116:119], v[154:157], v[182:185], v[116:119]
	v_mfma_f32_16x16x32_bf16 v[108:111], v[166:169], v[182:185], v[108:111]
	v_mfma_f32_16x16x32_bf16 v[100:103], v[154:157], v[190:193], v[100:103]
	v_mfma_f32_16x16x32_bf16 v[92:95], v[166:169], v[190:193], v[92:95]
	v_mfma_f32_16x16x32_bf16 v[84:87], v[154:157], v[198:201], v[84:87]
	v_mfma_f32_16x16x32_bf16 v[76:79], v[166:169], v[198:201], v[76:79]
	v_mfma_f32_16x16x32_bf16 v[112:115], v[202:205], v[170:173], 0
	v_mfma_f32_16x16x32_bf16 v[104:107], v[210:213], v[170:173], 0
	v_mfma_f32_16x16x32_bf16 v[96:99], v[202:205], v[178:181], 0
	v_mfma_f32_16x16x32_bf16 v[88:91], v[210:213], v[178:181], 0
	v_mfma_f32_16x16x32_bf16 v[80:83], v[202:205], v[186:189], 0
	v_mfma_f32_16x16x32_bf16 v[72:75], v[210:213], v[186:189], 0
	v_mfma_f32_16x16x32_bf16 v[68:71], v[202:205], v[194:197], 0
	v_mfma_f32_16x16x32_bf16 v[64:67], v[210:213], v[194:197], 0
	v_mfma_f32_16x16x32_bf16 v[112:115], v[206:209], v[174:177], v[112:115]
	v_mfma_f32_16x16x32_bf16 v[104:107], v[214:217], v[174:177], v[104:107]
	v_mfma_f32_16x16x32_bf16 v[96:99], v[206:209], v[182:185], v[96:99]
	v_mfma_f32_16x16x32_bf16 v[88:91], v[214:217], v[182:185], v[88:91]
	v_mfma_f32_16x16x32_bf16 v[80:83], v[206:209], v[190:193], v[80:83]
	v_mfma_f32_16x16x32_bf16 v[72:75], v[214:217], v[190:193], v[72:75]
	v_mfma_f32_16x16x32_bf16 v[68:71], v[206:209], v[198:201], v[68:71]
	v_mfma_f32_16x16x32_bf16 v[64:67], v[214:217], v[198:201], v[64:67]
	s_barrier
	ds_read_b128 v[170:173], v163 offset:16384
	ds_read_b128 v[174:177], v163 offset:17408
	ds_read_b128 v[178:181], v163 offset:18432
	ds_read_b128 v[182:185], v163 offset:19456
	ds_read_b128 v[186:189], v163 offset:20480
	ds_read_b128 v[190:193], v163 offset:21504
	ds_read_b128 v[194:197], v163 offset:22528
	ds_read_b128 v[198:201], v163 offset:23552
	s_add_i32 s45, s66, s21
	s_mov_b32 m0, s45
	v_lshl_add_u64 v[218:219], s[54:55], 0, v[138:139]
	global_load_lds_dwordx4 v[218:219], off
	s_add_i32 m0, s45, 0x2000
	v_lshl_add_u64 v[220:221], s[54:55], 0, v[142:143]
	global_load_lds_dwordx4 v[220:221], off
	s_mov_b32 m0, s33
	v_lshl_add_u64 v[222:223], s[56:57], 0, v[136:137]
	global_load_lds_dwordx4 v[222:223], off
	s_mov_b32 m0, s35
	v_lshl_add_u64 v[224:225], s[56:57], 0, v[140:141]
	global_load_lds_dwordx4 v[224:225], off
	s_add_u32 s78, s54, 0x40000
	s_addc_u32 s79, s55, 0
	s_add_i32 s45, s67, s21
	s_mov_b32 m0, s45
	v_lshl_add_u64 v[240:241], s[78:79], 0, v[138:139]
	global_load_lds_dwordx4 v[240:241], off
	s_add_i32 m0, s45, 0x2000
	v_lshl_add_u64 v[240:241], s[78:79], 0, v[142:143]
	global_load_lds_dwordx4 v[240:241], off
	s_waitcnt vmcnt(8) lgkmcnt(0)
	s_barrier
	v_mfma_f32_16x16x32_bf16 v[60:63], v[150:153], v[170:173], 0
	v_mfma_f32_16x16x32_bf16 v[56:59], v[158:161], v[170:173], 0
	v_mfma_f32_16x16x32_bf16 v[52:55], v[150:153], v[178:181], 0
	v_mfma_f32_16x16x32_bf16 v[44:47], v[158:161], v[178:181], 0
	v_mfma_f32_16x16x32_bf16 v[36:39], v[150:153], v[186:189], 0
	v_mfma_f32_16x16x32_bf16 v[28:31], v[158:161], v[186:189], 0
	v_mfma_f32_16x16x32_bf16 v[20:23], v[150:153], v[194:197], 0
	v_mfma_f32_16x16x32_bf16 v[12:15], v[158:161], v[194:197], 0
	v_mfma_f32_16x16x32_bf16 v[60:63], v[154:157], v[174:177], v[60:63]
	v_mfma_f32_16x16x32_bf16 v[56:59], v[166:169], v[174:177], v[56:59]
	v_mfma_f32_16x16x32_bf16 v[52:55], v[154:157], v[182:185], v[52:55]
	v_mfma_f32_16x16x32_bf16 v[44:47], v[166:169], v[182:185], v[44:47]
	v_mfma_f32_16x16x32_bf16 v[36:39], v[154:157], v[190:193], v[36:39]
	v_mfma_f32_16x16x32_bf16 v[28:31], v[166:169], v[190:193], v[28:31]
	v_mfma_f32_16x16x32_bf16 v[20:23], v[154:157], v[198:201], v[20:23]
	v_mfma_f32_16x16x32_bf16 v[12:15], v[166:169], v[198:201], v[12:15]
	v_mfma_f32_16x16x32_bf16 v[48:51], v[202:205], v[170:173], 0
	v_mfma_f32_16x16x32_bf16 v[40:43], v[210:213], v[170:173], 0
	v_mfma_f32_16x16x32_bf16 v[32:35], v[202:205], v[178:181], 0
	v_mfma_f32_16x16x32_bf16 v[24:27], v[210:213], v[178:181], 0
	v_mfma_f32_16x16x32_bf16 v[16:19], v[202:205], v[186:189], 0
	v_mfma_f32_16x16x32_bf16 v[8:11], v[210:213], v[186:189], 0
	v_mfma_f32_16x16x32_bf16 v[4:7], v[202:205], v[194:197], 0
	v_mfma_f32_16x16x32_bf16 v[0:3], v[210:213], v[194:197], 0
	v_mfma_f32_16x16x32_bf16 v[48:51], v[206:209], v[174:177], v[48:51]
	v_mfma_f32_16x16x32_bf16 v[40:43], v[214:217], v[174:177], v[40:43]
	v_mfma_f32_16x16x32_bf16 v[32:35], v[206:209], v[182:185], v[32:35]
	v_mfma_f32_16x16x32_bf16 v[24:27], v[214:217], v[182:185], v[24:27]
	v_mfma_f32_16x16x32_bf16 v[16:19], v[206:209], v[190:193], v[16:19]
	v_mfma_f32_16x16x32_bf16 v[8:11], v[214:217], v[190:193], v[8:11]
	v_mfma_f32_16x16x32_bf16 v[4:7], v[206:209], v[198:201], v[4:7]
	v_mfma_f32_16x16x32_bf16 v[0:3], v[214:217], v[198:201], v[0:3]
	s_barrier
; #define PG8_STAGE(bufoff, gbase, voff) do { _Pragma("unroll") for (int _i = 0; _i < 2; ++_i) \
;         __builtin_amdgcn_global_load_lds((const unsigned*)((const char*)(gbase) + (voff)[_i]), (LAS unsigned*)(lds + (bufoff) + ldsw + _i * 8192), 16, 0, 0); } while (0)
; #define PG8_LDA(dst, b, h) do { _Pragma("unroll") for (int m = 0; m < 4; ++m) _Pragma("unroll") for (int k = 0; k < 2; ++k) dst[m][k] = *(const LAS bf16x8*)(lds + PG8_SA(b, h) + aoff + m * 2048 + k * 1024); } while (0)
; #define PG8_LDB(dst, b, h) do { _Pragma("unroll") for (int n = 0; n < 2; ++n) _Pragma("unroll") for (int k = 0; k < 2; ++k) dst[n][k] = *(const LAS bf16x8*)(lds + PG8_SB(b, h) + boff + n * 2048 + k * 1024); } while (0)
; #define PG8_MMA(ai, bj, At, Bt) do { __builtin_amdgcn_s_setprio(1); _Pragma("unroll") for (int m = 0; m < 4; ++m) _Pragma("unroll") for (int n = 0; n < 2; ++n) _Pragma("unroll") for (int k = 0; k < 2; ++k) \
;         acc[ai][bj][m][n] = __builtin_amdgcn_mfma_f32_16x16x32_bf16(Bt[n][k], At[m][k], acc[ai][bj][m][n], 0, 0, 0); __builtin_amdgcn_s_setprio(0); } while (0)
; #define PG8_WAIT_V(n) asm volatile("s_waitcnt vmcnt(" #n ")" ::: "memory")
; #define PG8_WAIT_L(n) asm volatile("s_waitcnt lgkmcnt(" #n ")" ::: "memory")
; #define PG8_BAR __builtin_amdgcn_s_barrier()
; #define PG8_SCHED __builtin_amdgcn_sched_barrier(0)
; template <class Epi>
; __device__ __forceinline__ void gemm_phase(LAS unsigned char* lds, const Gemm g, const StaticOrder& S, const Epi& E) {
;     ...
;             PG8_LDB(B0, 1, 0); PG8_SCHED; PG8_LDA(At, 1, 0); PG8_STAGE(PG8_SA(0, 1), a2 + hstepA, voffA);
;             PG8_WAIT_L(8); PG8_BAR; PG8_WAIT_L(0); PG8_MMA(0, 0, At, B0); PG8_BAR; PG8_SCHED;
;             PG8_LDB(B1, 1, 1); PG8_STAGE(PG8_SB(1, 0), b3, voffB);
;             PG8_BAR; PG8_WAIT_L(0); PG8_MMA(0, 1, At, B1); PG8_BAR;
;             PG8_LDA(At, 1, 1); PG8_STAGE(PG8_SA(1, 0), a3, voffA);
;             PG8_BAR; PG8_WAIT_L(0); PG8_MMA(1, 0, At, B0); PG8_BAR; PG8_SCHED;
;             PG8_STAGE(PG8_SB(1, 1), b3 + hstepB, voffB);
;             PG8_WAIT_V(6); PG8_BAR; PG8_MMA(1, 1, At, B1); PG8_BAR;
	s_add_i32 s45, 0, 0x18000
	v_add_u32_e32 v165, s45, v135
	ds_read_b128 v[150:153], v165
	ds_read_b128 v[154:157], v165 offset:1024
	ds_read_b128 v[158:161], v165 offset:2048
	ds_read_b128 v[166:169], v165 offset:3072
	ds_read_b128 v[170:173], v163 offset:32768
	ds_read_b128 v[174:177], v163 offset:33792
	ds_read_b128 v[178:181], v163 offset:34816
	ds_read_b128 v[182:185], v163 offset:35840
	ds_read_b128 v[186:189], v163 offset:36864
	ds_read_b128 v[190:193], v163 offset:37888
	ds_read_b128 v[194:197], v163 offset:38912
	ds_read_b128 v[198:201], v163 offset:39936
	s_add_i32 s98, 0, 0x1c000
	v_add_u32_e32 v246, s98, v135
	ds_read_b128 v[202:205], v246
	ds_read_b128 v[206:209], v246 offset:1024
	ds_read_b128 v[210:213], v246 offset:2048
	ds_read_b128 v[214:217], v246 offset:3072
	s_add_u32 s56, s56, 0x40000
	s_addc_u32 s57, s57, 0
	s_mov_b32 m0, s58
	v_lshl_add_u64 v[244:245], s[56:57], 0, v[136:137]
	global_load_lds_dwordx4 v[244:245], off
	s_mov_b32 m0, s59
	v_lshl_add_u64 v[244:245], s[56:57], 0, v[140:141]
	global_load_lds_dwordx4 v[244:245], off
	s_waitcnt vmcnt(8) lgkmcnt(0)
	s_barrier
	v_mfma_f32_16x16x32_bf16 v[124:127], v[150:153], v[170:173], v[124:127]
	v_mfma_f32_16x16x32_bf16 v[120:123], v[158:161], v[170:173], v[120:123]
	v_mfma_f32_16x16x32_bf16 v[116:119], v[150:153], v[178:181], v[116:119]
	v_mfma_f32_16x16x32_bf16 v[108:111], v[158:161], v[178:181], v[108:111]
	v_mfma_f32_16x16x32_bf16 v[100:103], v[150:153], v[186:189], v[100:103]
	v_mfma_f32_16x16x32_bf16 v[92:95], v[158:161], v[186:189], v[92:95]
	v_mfma_f32_16x16x32_bf16 v[84:87], v[150:153], v[194:197], v[84:87]
	v_mfma_f32_16x16x32_bf16 v[76:79], v[158:161], v[194:197], v[76:79]
	v_mfma_f32_16x16x32_bf16 v[124:127], v[154:157], v[174:177], v[124:127]
	v_mfma_f32_16x16x32_bf16 v[120:123], v[166:169], v[174:177], v[120:123]
	v_mfma_f32_16x16x32_bf16 v[116:119], v[154:157], v[182:185], v[116:119]
	v_mfma_f32_16x16x32_bf16 v[108:111], v[166:169], v[182:185], v[108:111]
	v_mfma_f32_16x16x32_bf16 v[100:103], v[154:157], v[190:193], v[100:103]
	v_mfma_f32_16x16x32_bf16 v[92:95], v[166:169], v[190:193], v[92:95]
	v_mfma_f32_16x16x32_bf16 v[84:87], v[154:157], v[198:201], v[84:87]
	v_mfma_f32_16x16x32_bf16 v[76:79], v[166:169], v[198:201], v[76:79]
	v_mfma_f32_16x16x32_bf16 v[112:115], v[202:205], v[170:173], v[112:115]
	v_mfma_f32_16x16x32_bf16 v[104:107], v[210:213], v[170:173], v[104:107]
	v_mfma_f32_16x16x32_bf16 v[96:99], v[202:205], v[178:181], v[96:99]
	v_mfma_f32_16x16x32_bf16 v[88:91], v[210:213], v[178:181], v[88:91]
	v_mfma_f32_16x16x32_bf16 v[80:83], v[202:205], v[186:189], v[80:83]
	v_mfma_f32_16x16x32_bf16 v[72:75], v[210:213], v[186:189], v[72:75]
	v_mfma_f32_16x16x32_bf16 v[68:71], v[202:205], v[194:197], v[68:71]
	v_mfma_f32_16x16x32_bf16 v[64:67], v[210:213], v[194:197], v[64:67]
	v_mfma_f32_16x16x32_bf16 v[112:115], v[206:209], v[174:177], v[112:115]
	v_mfma_f32_16x16x32_bf16 v[104:107], v[214:217], v[174:177], v[104:107]
	v_mfma_f32_16x16x32_bf16 v[96:99], v[206:209], v[182:185], v[96:99]
	v_mfma_f32_16x16x32_bf16 v[88:91], v[214:217], v[182:185], v[88:91]
	v_mfma_f32_16x16x32_bf16 v[80:83], v[206:209], v[190:193], v[80:83]
	v_mfma_f32_16x16x32_bf16 v[72:75], v[214:217], v[190:193], v[72:75]
	v_mfma_f32_16x16x32_bf16 v[68:71], v[206:209], v[198:201], v[68:71]
	v_mfma_f32_16x16x32_bf16 v[64:67], v[214:217], v[198:201], v[64:67]
	s_barrier
	ds_read_b128 v[170:173], v163 offset:49152
	ds_read_b128 v[174:177], v163 offset:50176
	ds_read_b128 v[178:181], v163 offset:51200
	ds_read_b128 v[182:185], v163 offset:52224
	ds_read_b128 v[186:189], v163 offset:53248
	ds_read_b128 v[190:193], v163 offset:54272
	ds_read_b128 v[194:197], v163 offset:55296
	ds_read_b128 v[198:201], v163 offset:56320
	s_add_i32 s45, s45, s21
	s_mov_b32 m0, s45
	v_lshl_add_u64 v[218:219], v[218:219], 0, s[12:13]
	global_load_lds_dwordx4 v[218:219], off
	s_add_i32 m0, s45, 0x2000
	v_lshl_add_u64 v[218:219], v[220:221], 0, s[12:13]
	global_load_lds_dwordx4 v[218:219], off
	s_mov_b32 m0, s60
	v_lshl_add_u64 v[218:219], v[222:223], 0, s[12:13]
	global_load_lds_dwordx4 v[218:219], off
	s_mov_b32 m0, s61
	v_lshl_add_u64 v[218:219], v[224:225], 0, s[12:13]
	global_load_lds_dwordx4 v[218:219], off
	s_add_u32 s54, s54, 0x40080
	s_addc_u32 s55, s55, 0
	s_add_i32 s45, s98, s21
	s_mov_b32 m0, s45
	v_lshl_add_u64 v[240:241], s[54:55], 0, v[138:139]
	global_load_lds_dwordx4 v[240:241], off
	s_add_i32 m0, s45, 0x2000
	v_lshl_add_u64 v[240:241], s[54:55], 0, v[142:143]
	global_load_lds_dwordx4 v[240:241], off
	s_waitcnt vmcnt(8) lgkmcnt(0)
	s_barrier
	v_mfma_f32_16x16x32_bf16 v[60:63], v[150:153], v[170:173], v[60:63]
	v_mfma_f32_16x16x32_bf16 v[56:59], v[158:161], v[170:173], v[56:59]
	v_mfma_f32_16x16x32_bf16 v[52:55], v[150:153], v[178:181], v[52:55]
	v_mfma_f32_16x16x32_bf16 v[44:47], v[158:161], v[178:181], v[44:47]
	v_mfma_f32_16x16x32_bf16 v[36:39], v[150:153], v[186:189], v[36:39]
	v_mfma_f32_16x16x32_bf16 v[28:31], v[158:161], v[186:189], v[28:31]
	v_mfma_f32_16x16x32_bf16 v[20:23], v[150:153], v[194:197], v[20:23]
	v_mfma_f32_16x16x32_bf16 v[12:15], v[158:161], v[194:197], v[12:15]
	v_mfma_f32_16x16x32_bf16 v[60:63], v[154:157], v[174:177], v[60:63]
	v_mfma_f32_16x16x32_bf16 v[56:59], v[166:169], v[174:177], v[56:59]
	v_mfma_f32_16x16x32_bf16 v[52:55], v[154:157], v[182:185], v[52:55]
	v_mfma_f32_16x16x32_bf16 v[44:47], v[166:169], v[182:185], v[44:47]
	v_mfma_f32_16x16x32_bf16 v[36:39], v[154:157], v[190:193], v[36:39]
	v_mfma_f32_16x16x32_bf16 v[28:31], v[166:169], v[190:193], v[28:31]
	v_mfma_f32_16x16x32_bf16 v[20:23], v[154:157], v[198:201], v[20:23]
	v_mfma_f32_16x16x32_bf16 v[12:15], v[166:169], v[198:201], v[12:15]
	v_mfma_f32_16x16x32_bf16 v[48:51], v[202:205], v[170:173], v[48:51]
	v_mfma_f32_16x16x32_bf16 v[40:43], v[210:213], v[170:173], v[40:43]
	v_mfma_f32_16x16x32_bf16 v[32:35], v[202:205], v[178:181], v[32:35]
	v_mfma_f32_16x16x32_bf16 v[24:27], v[210:213], v[178:181], v[24:27]
	v_mfma_f32_16x16x32_bf16 v[16:19], v[202:205], v[186:189], v[16:19]
	v_mfma_f32_16x16x32_bf16 v[8:11], v[210:213], v[186:189], v[8:11]
	v_mfma_f32_16x16x32_bf16 v[4:7], v[202:205], v[194:197], v[4:7]
	v_mfma_f32_16x16x32_bf16 v[0:3], v[210:213], v[194:197], v[0:3]
	v_mfma_f32_16x16x32_bf16 v[48:51], v[206:209], v[174:177], v[48:51]
	v_mfma_f32_16x16x32_bf16 v[40:43], v[214:217], v[174:177], v[40:43]
	v_mfma_f32_16x16x32_bf16 v[32:35], v[206:209], v[182:185], v[32:35]
	v_mfma_f32_16x16x32_bf16 v[24:27], v[214:217], v[182:185], v[24:27]
	v_mfma_f32_16x16x32_bf16 v[16:19], v[206:209], v[190:193], v[16:19]
	v_mfma_f32_16x16x32_bf16 v[8:11], v[214:217], v[190:193], v[8:11]
	v_mfma_f32_16x16x32_bf16 v[4:7], v[206:209], v[198:201], v[4:7]
	v_mfma_f32_16x16x32_bf16 v[0:3], v[214:217], v[198:201], v[0:3]
	s_add_u32 s50, s50, 0x100
	s_addc_u32 s51, s51, 0
	s_add_u32 s41, s41, 0x100
	s_addc_u32 s43, s43, 0
	s_cmp_ge_i32 s77, s76
	s_mov_b32 s45, s77
	s_barrier
